# hand-scheduled K-loop (reads/LDS-DMA interleaved with MFMAs) now on all four big GEMM phases (P2, P7, P9, P10)
# speedup vs baseline: 1.0182x; 1.0182x over previous
.LBB0_113:
	v_add_u32_e32 v172, v153, v170
	v_add_u32_e32 v173, v153, v171
	v_add_u32_e32 v174, v169, v170
	v_add_u32_e32 v175, v169, v171
	s_mov_b64 s[100:101], 0x80
	v_lshl_add_u64 v[240:241], v[128:129], 0, s[100:101]
	s_mov_b64 s[100:101], 0x20080
	v_lshl_add_u64 v[242:243], v[128:129], 0, s[100:101]
	s_mov_b64 s[100:101], 0x40080
	v_lshl_add_u64 v[244:245], v[128:129], 0, s[100:101]
	s_mov_b64 s[100:101], 0x60080
	v_lshl_add_u64 v[246:247], v[128:129], 0, s[100:101]
	s_mov_b64 s[100:101], 0x80
	v_lshl_add_u64 v[138:139], v[130:131], 0, s[100:101]
	s_mov_b64 s[100:101], 0x20080
	v_lshl_add_u64 v[140:141], v[130:131], 0, s[100:101]
	s_mov_b64 s[100:101], 0x40080
	v_lshl_add_u64 v[250:251], v[130:131], 0, s[100:101]
	s_mov_b64 s[100:101], 0x60080
	v_lshl_add_u64 v[252:253], v[130:131], 0, s[100:101]
	v_readfirstlane_b32 s100, v145
	v_readfirstlane_b32 s101, v146
	s_nop 3
	ds_read_b128 v[176:179], v172 offset:0
	ds_read_b128 v[180:183], v172 offset:2048
	ds_read_b128 v[184:187], v172 offset:4096
	ds_read_b128 v[188:191], v172 offset:6144
	ds_read_b128 v[208:211], v174 offset:0
	ds_read_b128 v[212:215], v174 offset:2048
	ds_read_b128 v[216:219], v174 offset:4096
	ds_read_b128 v[220:223], v174 offset:6144
	s_add_u32 m0, s100, 0x8000
	s_nop 0
	global_load_lds_dwordx4 v[240:241], off
	v_lshl_add_u64 v[240:241], v[240:241], 0, s[34:35]
	s_add_u32 m0, s100, 0xa000
	s_nop 0
	global_load_lds_dwordx4 v[242:243], off
	v_lshl_add_u64 v[242:243], v[242:243], 0, s[34:35]
	s_add_u32 m0, s100, 0xc000
	s_nop 0
	global_load_lds_dwordx4 v[244:245], off
	v_lshl_add_u64 v[244:245], v[244:245], 0, s[34:35]
	s_add_u32 m0, s100, 0xe000
	s_nop 0
	global_load_lds_dwordx4 v[246:247], off
	v_lshl_add_u64 v[246:247], v[246:247], 0, s[34:35]
	s_waitcnt lgkmcnt(0)
	v_mfma_f32_16x16x32_bf16 v[120:123], v[208:211], v[176:179], v[120:123]
	ds_read_b128 v[224:227], v174 offset:8192
	v_mfma_f32_16x16x32_bf16 v[112:115], v[212:215], v[176:179], v[112:115]
	ds_read_b128 v[228:231], v174 offset:10240
	v_mfma_f32_16x16x32_bf16 v[124:127], v[216:219], v[176:179], v[124:127]
	ds_read_b128 v[232:235], v174 offset:12288
	v_mfma_f32_16x16x32_bf16 v[116:119], v[220:223], v[176:179], v[116:119]
	ds_read_b128 v[236:239], v174 offset:14336
	v_mfma_f32_16x16x32_bf16 v[88:91], v[208:211], v[180:183], v[88:91]
	s_add_u32 m0, s101, 0x8000
	v_mfma_f32_16x16x32_bf16 v[80:83], v[212:215], v[180:183], v[80:83]
	global_load_lds_dwordx4 v[138:139], off
	v_lshl_add_u64 v[138:139], v[138:139], 0, s[34:35]
	v_mfma_f32_16x16x32_bf16 v[92:95], v[216:219], v[180:183], v[92:95]
	s_add_u32 m0, s101, 0xa000
	v_mfma_f32_16x16x32_bf16 v[84:87], v[220:223], v[180:183], v[84:87]
	global_load_lds_dwordx4 v[140:141], off
	v_lshl_add_u64 v[140:141], v[140:141], 0, s[34:35]
	v_mfma_f32_16x16x32_bf16 v[56:59], v[208:211], v[184:187], v[56:59]
	s_add_u32 m0, s101, 0xc000
	v_mfma_f32_16x16x32_bf16 v[48:51], v[212:215], v[184:187], v[48:51]
	global_load_lds_dwordx4 v[250:251], off
	v_lshl_add_u64 v[250:251], v[250:251], 0, s[34:35]
	v_mfma_f32_16x16x32_bf16 v[60:63], v[216:219], v[184:187], v[60:63]
	s_add_u32 m0, s101, 0xe000
	v_mfma_f32_16x16x32_bf16 v[52:55], v[220:223], v[184:187], v[52:55]
	global_load_lds_dwordx4 v[252:253], off
	v_lshl_add_u64 v[252:253], v[252:253], 0, s[34:35]
	v_mfma_f32_16x16x32_bf16 v[24:27], v[208:211], v[188:191], v[24:27]
	v_mfma_f32_16x16x32_bf16 v[16:19], v[212:215], v[188:191], v[16:19]
	v_mfma_f32_16x16x32_bf16 v[28:31], v[216:219], v[188:191], v[28:31]
	v_mfma_f32_16x16x32_bf16 v[20:23], v[220:223], v[188:191], v[20:23]
	s_waitcnt lgkmcnt(0)
	v_mfma_f32_16x16x32_bf16 v[104:107], v[224:227], v[176:179], v[104:107]
	ds_read_b128 v[192:195], v173 offset:0
	v_mfma_f32_16x16x32_bf16 v[96:99], v[228:231], v[176:179], v[96:99]
	ds_read_b128 v[196:199], v173 offset:2048
	v_mfma_f32_16x16x32_bf16 v[108:111], v[232:235], v[176:179], v[108:111]
	ds_read_b128 v[200:203], v173 offset:4096
	v_mfma_f32_16x16x32_bf16 v[100:103], v[236:239], v[176:179], v[100:103]
	ds_read_b128 v[204:207], v173 offset:6144
	v_mfma_f32_16x16x32_bf16 v[72:75], v[224:227], v[180:183], v[72:75]
	ds_read_b128 v[208:211], v175 offset:0
	v_mfma_f32_16x16x32_bf16 v[64:67], v[228:231], v[180:183], v[64:67]
	ds_read_b128 v[212:215], v175 offset:2048
	v_mfma_f32_16x16x32_bf16 v[76:79], v[232:235], v[180:183], v[76:79]
	ds_read_b128 v[216:219], v175 offset:4096
	v_mfma_f32_16x16x32_bf16 v[68:71], v[236:239], v[180:183], v[68:71]
	ds_read_b128 v[220:223], v175 offset:6144
	v_mfma_f32_16x16x32_bf16 v[40:43], v[224:227], v[184:187], v[40:43]
	v_mfma_f32_16x16x32_bf16 v[32:35], v[228:231], v[184:187], v[32:35]
	v_mfma_f32_16x16x32_bf16 v[44:47], v[232:235], v[184:187], v[44:47]
	v_mfma_f32_16x16x32_bf16 v[36:39], v[236:239], v[184:187], v[36:39]
	v_mfma_f32_16x16x32_bf16 v[8:11], v[224:227], v[188:191], v[8:11]
	v_mfma_f32_16x16x32_bf16 v[0:3], v[228:231], v[188:191], v[0:3]
	v_mfma_f32_16x16x32_bf16 v[12:15], v[232:235], v[188:191], v[12:15]
	v_mfma_f32_16x16x32_bf16 v[4:7], v[236:239], v[188:191], v[4:7]
	s_waitcnt lgkmcnt(0)
	v_mfma_f32_16x16x32_bf16 v[120:123], v[208:211], v[192:195], v[120:123]
	ds_read_b128 v[224:227], v175 offset:8192
	v_mfma_f32_16x16x32_bf16 v[112:115], v[212:215], v[192:195], v[112:115]
	ds_read_b128 v[228:231], v175 offset:10240
	v_mfma_f32_16x16x32_bf16 v[124:127], v[216:219], v[192:195], v[124:127]
	ds_read_b128 v[232:235], v175 offset:12288
	v_mfma_f32_16x16x32_bf16 v[116:119], v[220:223], v[192:195], v[116:119]
	ds_read_b128 v[236:239], v175 offset:14336
	v_mfma_f32_16x16x32_bf16 v[88:91], v[208:211], v[196:199], v[88:91]
	v_mfma_f32_16x16x32_bf16 v[80:83], v[212:215], v[196:199], v[80:83]
	v_mfma_f32_16x16x32_bf16 v[92:95], v[216:219], v[196:199], v[92:95]
	v_mfma_f32_16x16x32_bf16 v[84:87], v[220:223], v[196:199], v[84:87]
	v_mfma_f32_16x16x32_bf16 v[56:59], v[208:211], v[200:203], v[56:59]
	v_mfma_f32_16x16x32_bf16 v[48:51], v[212:215], v[200:203], v[48:51]
	v_mfma_f32_16x16x32_bf16 v[60:63], v[216:219], v[200:203], v[60:63]
	v_mfma_f32_16x16x32_bf16 v[52:55], v[220:223], v[200:203], v[52:55]
	v_mfma_f32_16x16x32_bf16 v[24:27], v[208:211], v[204:207], v[24:27]
	v_mfma_f32_16x16x32_bf16 v[16:19], v[212:215], v[204:207], v[16:19]
	v_mfma_f32_16x16x32_bf16 v[28:31], v[216:219], v[204:207], v[28:31]
	v_mfma_f32_16x16x32_bf16 v[20:23], v[220:223], v[204:207], v[20:23]
	s_waitcnt lgkmcnt(0)
	s_waitcnt vmcnt(0)
	s_barrier
	s_mov_b32 s7, 7
.Lgemm_p2_loop:
	v_mfma_f32_16x16x32_bf16 v[104:107], v[224:227], v[192:195], v[104:107]
	ds_read_b128 v[176:179], v172 offset:32768
	v_mfma_f32_16x16x32_bf16 v[96:99], v[228:231], v[192:195], v[96:99]
	ds_read_b128 v[180:183], v172 offset:34816
	v_mfma_f32_16x16x32_bf16 v[108:111], v[232:235], v[192:195], v[108:111]
	ds_read_b128 v[184:187], v172 offset:36864
	v_mfma_f32_16x16x32_bf16 v[100:103], v[236:239], v[192:195], v[100:103]
	ds_read_b128 v[188:191], v172 offset:38912
	v_mfma_f32_16x16x32_bf16 v[72:75], v[224:227], v[196:199], v[72:75]
	ds_read_b128 v[208:211], v174 offset:32768
	v_mfma_f32_16x16x32_bf16 v[64:67], v[228:231], v[196:199], v[64:67]
	ds_read_b128 v[212:215], v174 offset:34816
	v_mfma_f32_16x16x32_bf16 v[76:79], v[232:235], v[196:199], v[76:79]
	ds_read_b128 v[216:219], v174 offset:36864
	v_mfma_f32_16x16x32_bf16 v[68:71], v[236:239], v[196:199], v[68:71]
	ds_read_b128 v[220:223], v174 offset:38912
	v_mfma_f32_16x16x32_bf16 v[40:43], v[224:227], v[200:203], v[40:43]
	s_mov_b32 m0, s100
	v_mfma_f32_16x16x32_bf16 v[32:35], v[228:231], v[200:203], v[32:35]
	global_load_lds_dwordx4 v[240:241], off
	v_lshl_add_u64 v[240:241], v[240:241], 0, s[34:35]
	v_mfma_f32_16x16x32_bf16 v[44:47], v[232:235], v[200:203], v[44:47]
	s_add_u32 m0, s100, 0x2000
	v_mfma_f32_16x16x32_bf16 v[36:39], v[236:239], v[200:203], v[36:39]
	global_load_lds_dwordx4 v[242:243], off
	v_lshl_add_u64 v[242:243], v[242:243], 0, s[34:35]
	v_mfma_f32_16x16x32_bf16 v[8:11], v[224:227], v[204:207], v[8:11]
	s_add_u32 m0, s100, 0x4000
	v_mfma_f32_16x16x32_bf16 v[0:3], v[228:231], v[204:207], v[0:3]
	global_load_lds_dwordx4 v[244:245], off
	v_lshl_add_u64 v[244:245], v[244:245], 0, s[34:35]
	v_mfma_f32_16x16x32_bf16 v[12:15], v[232:235], v[204:207], v[12:15]
	s_add_u32 m0, s100, 0x6000
	v_mfma_f32_16x16x32_bf16 v[4:7], v[236:239], v[204:207], v[4:7]
	global_load_lds_dwordx4 v[246:247], off
	v_lshl_add_u64 v[246:247], v[246:247], 0, s[34:35]
	s_waitcnt lgkmcnt(0)
	v_mfma_f32_16x16x32_bf16 v[120:123], v[208:211], v[176:179], v[120:123]
	ds_read_b128 v[224:227], v174 offset:40960
	v_mfma_f32_16x16x32_bf16 v[112:115], v[212:215], v[176:179], v[112:115]
	ds_read_b128 v[228:231], v174 offset:43008
	v_mfma_f32_16x16x32_bf16 v[124:127], v[216:219], v[176:179], v[124:127]
	ds_read_b128 v[232:235], v174 offset:45056
	v_mfma_f32_16x16x32_bf16 v[116:119], v[220:223], v[176:179], v[116:119]
	ds_read_b128 v[236:239], v174 offset:47104
	v_mfma_f32_16x16x32_bf16 v[88:91], v[208:211], v[180:183], v[88:91]
	s_mov_b32 m0, s101
	v_mfma_f32_16x16x32_bf16 v[80:83], v[212:215], v[180:183], v[80:83]
	global_load_lds_dwordx4 v[138:139], off
	v_lshl_add_u64 v[138:139], v[138:139], 0, s[34:35]
	v_mfma_f32_16x16x32_bf16 v[92:95], v[216:219], v[180:183], v[92:95]
	s_add_u32 m0, s101, 0x2000
	v_mfma_f32_16x16x32_bf16 v[84:87], v[220:223], v[180:183], v[84:87]
	global_load_lds_dwordx4 v[140:141], off
	v_lshl_add_u64 v[140:141], v[140:141], 0, s[34:35]
	v_mfma_f32_16x16x32_bf16 v[56:59], v[208:211], v[184:187], v[56:59]
	s_add_u32 m0, s101, 0x4000
	v_mfma_f32_16x16x32_bf16 v[48:51], v[212:215], v[184:187], v[48:51]
	global_load_lds_dwordx4 v[250:251], off
	v_lshl_add_u64 v[250:251], v[250:251], 0, s[34:35]
	v_mfma_f32_16x16x32_bf16 v[60:63], v[216:219], v[184:187], v[60:63]
	s_add_u32 m0, s101, 0x6000
	v_mfma_f32_16x16x32_bf16 v[52:55], v[220:223], v[184:187], v[52:55]
	global_load_lds_dwordx4 v[252:253], off
	v_lshl_add_u64 v[252:253], v[252:253], 0, s[34:35]
	v_mfma_f32_16x16x32_bf16 v[24:27], v[208:211], v[188:191], v[24:27]
	v_mfma_f32_16x16x32_bf16 v[16:19], v[212:215], v[188:191], v[16:19]
	v_mfma_f32_16x16x32_bf16 v[28:31], v[216:219], v[188:191], v[28:31]
	v_mfma_f32_16x16x32_bf16 v[20:23], v[220:223], v[188:191], v[20:23]
	s_waitcnt lgkmcnt(0)
	v_mfma_f32_16x16x32_bf16 v[104:107], v[224:227], v[176:179], v[104:107]
	ds_read_b128 v[192:195], v173 offset:32768
	v_mfma_f32_16x16x32_bf16 v[96:99], v[228:231], v[176:179], v[96:99]
	ds_read_b128 v[196:199], v173 offset:34816
	v_mfma_f32_16x16x32_bf16 v[108:111], v[232:235], v[176:179], v[108:111]
	ds_read_b128 v[200:203], v173 offset:36864
	v_mfma_f32_16x16x32_bf16 v[100:103], v[236:239], v[176:179], v[100:103]
	ds_read_b128 v[204:207], v173 offset:38912
	v_mfma_f32_16x16x32_bf16 v[72:75], v[224:227], v[180:183], v[72:75]
	ds_read_b128 v[208:211], v175 offset:32768
	v_mfma_f32_16x16x32_bf16 v[64:67], v[228:231], v[180:183], v[64:67]
	ds_read_b128 v[212:215], v175 offset:34816
	v_mfma_f32_16x16x32_bf16 v[76:79], v[232:235], v[180:183], v[76:79]
	ds_read_b128 v[216:219], v175 offset:36864
	v_mfma_f32_16x16x32_bf16 v[68:71], v[236:239], v[180:183], v[68:71]
	ds_read_b128 v[220:223], v175 offset:38912
	v_mfma_f32_16x16x32_bf16 v[40:43], v[224:227], v[184:187], v[40:43]
	v_mfma_f32_16x16x32_bf16 v[32:35], v[228:231], v[184:187], v[32:35]
	v_mfma_f32_16x16x32_bf16 v[44:47], v[232:235], v[184:187], v[44:47]
	v_mfma_f32_16x16x32_bf16 v[36:39], v[236:239], v[184:187], v[36:39]
	v_mfma_f32_16x16x32_bf16 v[8:11], v[224:227], v[188:191], v[8:11]
	v_mfma_f32_16x16x32_bf16 v[0:3], v[228:231], v[188:191], v[0:3]
	v_mfma_f32_16x16x32_bf16 v[12:15], v[232:235], v[188:191], v[12:15]
	v_mfma_f32_16x16x32_bf16 v[4:7], v[236:239], v[188:191], v[4:7]
	s_waitcnt lgkmcnt(0)
	v_mfma_f32_16x16x32_bf16 v[120:123], v[208:211], v[192:195], v[120:123]
	ds_read_b128 v[224:227], v175 offset:40960
	v_mfma_f32_16x16x32_bf16 v[112:115], v[212:215], v[192:195], v[112:115]
	ds_read_b128 v[228:231], v175 offset:43008
	v_mfma_f32_16x16x32_bf16 v[124:127], v[216:219], v[192:195], v[124:127]
	ds_read_b128 v[232:235], v175 offset:45056
	v_mfma_f32_16x16x32_bf16 v[116:119], v[220:223], v[192:195], v[116:119]
	ds_read_b128 v[236:239], v175 offset:47104
	v_mfma_f32_16x16x32_bf16 v[88:91], v[208:211], v[196:199], v[88:91]
	v_mfma_f32_16x16x32_bf16 v[80:83], v[212:215], v[196:199], v[80:83]
	v_mfma_f32_16x16x32_bf16 v[92:95], v[216:219], v[196:199], v[92:95]
	v_mfma_f32_16x16x32_bf16 v[84:87], v[220:223], v[196:199], v[84:87]
	v_mfma_f32_16x16x32_bf16 v[56:59], v[208:211], v[200:203], v[56:59]
	v_mfma_f32_16x16x32_bf16 v[48:51], v[212:215], v[200:203], v[48:51]
	v_mfma_f32_16x16x32_bf16 v[60:63], v[216:219], v[200:203], v[60:63]
	v_mfma_f32_16x16x32_bf16 v[52:55], v[220:223], v[200:203], v[52:55]
	v_mfma_f32_16x16x32_bf16 v[24:27], v[208:211], v[204:207], v[24:27]
	v_mfma_f32_16x16x32_bf16 v[16:19], v[212:215], v[204:207], v[16:19]
	v_mfma_f32_16x16x32_bf16 v[28:31], v[216:219], v[204:207], v[28:31]
	v_mfma_f32_16x16x32_bf16 v[20:23], v[220:223], v[204:207], v[20:23]
	s_waitcnt lgkmcnt(0)
	s_waitcnt vmcnt(0)
	s_barrier
	v_mfma_f32_16x16x32_bf16 v[104:107], v[224:227], v[192:195], v[104:107]
	ds_read_b128 v[176:179], v172 offset:0
	v_mfma_f32_16x16x32_bf16 v[96:99], v[228:231], v[192:195], v[96:99]
	ds_read_b128 v[180:183], v172 offset:2048
	v_mfma_f32_16x16x32_bf16 v[108:111], v[232:235], v[192:195], v[108:111]
	ds_read_b128 v[184:187], v172 offset:4096
	v_mfma_f32_16x16x32_bf16 v[100:103], v[236:239], v[192:195], v[100:103]
	ds_read_b128 v[188:191], v172 offset:6144
	v_mfma_f32_16x16x32_bf16 v[72:75], v[224:227], v[196:199], v[72:75]
	ds_read_b128 v[208:211], v174 offset:0
	v_mfma_f32_16x16x32_bf16 v[64:67], v[228:231], v[196:199], v[64:67]
	ds_read_b128 v[212:215], v174 offset:2048
	v_mfma_f32_16x16x32_bf16 v[76:79], v[232:235], v[196:199], v[76:79]
	ds_read_b128 v[216:219], v174 offset:4096
	v_mfma_f32_16x16x32_bf16 v[68:71], v[236:239], v[196:199], v[68:71]
	ds_read_b128 v[220:223], v174 offset:6144
	v_mfma_f32_16x16x32_bf16 v[40:43], v[224:227], v[200:203], v[40:43]
	s_add_u32 m0, s100, 0x8000
	v_mfma_f32_16x16x32_bf16 v[32:35], v[228:231], v[200:203], v[32:35]
	global_load_lds_dwordx4 v[240:241], off
	v_lshl_add_u64 v[240:241], v[240:241], 0, s[34:35]
	v_mfma_f32_16x16x32_bf16 v[44:47], v[232:235], v[200:203], v[44:47]
	s_add_u32 m0, s100, 0xa000
	v_mfma_f32_16x16x32_bf16 v[36:39], v[236:239], v[200:203], v[36:39]
	global_load_lds_dwordx4 v[242:243], off
	v_lshl_add_u64 v[242:243], v[242:243], 0, s[34:35]
	v_mfma_f32_16x16x32_bf16 v[8:11], v[224:227], v[204:207], v[8:11]
	s_add_u32 m0, s100, 0xc000
	v_mfma_f32_16x16x32_bf16 v[0:3], v[228:231], v[204:207], v[0:3]
	global_load_lds_dwordx4 v[244:245], off
	v_lshl_add_u64 v[244:245], v[244:245], 0, s[34:35]
	v_mfma_f32_16x16x32_bf16 v[12:15], v[232:235], v[204:207], v[12:15]
	s_add_u32 m0, s100, 0xe000
	v_mfma_f32_16x16x32_bf16 v[4:7], v[236:239], v[204:207], v[4:7]
	global_load_lds_dwordx4 v[246:247], off
	v_lshl_add_u64 v[246:247], v[246:247], 0, s[34:35]
	s_waitcnt lgkmcnt(0)
	v_mfma_f32_16x16x32_bf16 v[120:123], v[208:211], v[176:179], v[120:123]
	ds_read_b128 v[224:227], v174 offset:8192
	v_mfma_f32_16x16x32_bf16 v[112:115], v[212:215], v[176:179], v[112:115]
	ds_read_b128 v[228:231], v174 offset:10240
	v_mfma_f32_16x16x32_bf16 v[124:127], v[216:219], v[176:179], v[124:127]
	ds_read_b128 v[232:235], v174 offset:12288
	v_mfma_f32_16x16x32_bf16 v[116:119], v[220:223], v[176:179], v[116:119]
	ds_read_b128 v[236:239], v174 offset:14336
	v_mfma_f32_16x16x32_bf16 v[88:91], v[208:211], v[180:183], v[88:91]
	s_add_u32 m0, s101, 0x8000
	v_mfma_f32_16x16x32_bf16 v[80:83], v[212:215], v[180:183], v[80:83]
	global_load_lds_dwordx4 v[138:139], off
	v_lshl_add_u64 v[138:139], v[138:139], 0, s[34:35]
	v_mfma_f32_16x16x32_bf16 v[92:95], v[216:219], v[180:183], v[92:95]
	s_add_u32 m0, s101, 0xa000
	v_mfma_f32_16x16x32_bf16 v[84:87], v[220:223], v[180:183], v[84:87]
	global_load_lds_dwordx4 v[140:141], off
	v_lshl_add_u64 v[140:141], v[140:141], 0, s[34:35]
	v_mfma_f32_16x16x32_bf16 v[56:59], v[208:211], v[184:187], v[56:59]
	s_add_u32 m0, s101, 0xc000
	v_mfma_f32_16x16x32_bf16 v[48:51], v[212:215], v[184:187], v[48:51]
	global_load_lds_dwordx4 v[250:251], off
	v_lshl_add_u64 v[250:251], v[250:251], 0, s[34:35]
	v_mfma_f32_16x16x32_bf16 v[60:63], v[216:219], v[184:187], v[60:63]
	s_add_u32 m0, s101, 0xe000
	v_mfma_f32_16x16x32_bf16 v[52:55], v[220:223], v[184:187], v[52:55]
	global_load_lds_dwordx4 v[252:253], off
	v_lshl_add_u64 v[252:253], v[252:253], 0, s[34:35]
	v_mfma_f32_16x16x32_bf16 v[24:27], v[208:211], v[188:191], v[24:27]
	v_mfma_f32_16x16x32_bf16 v[16:19], v[212:215], v[188:191], v[16:19]
	v_mfma_f32_16x16x32_bf16 v[28:31], v[216:219], v[188:191], v[28:31]
	v_mfma_f32_16x16x32_bf16 v[20:23], v[220:223], v[188:191], v[20:23]
	s_waitcnt lgkmcnt(0)
	v_mfma_f32_16x16x32_bf16 v[104:107], v[224:227], v[176:179], v[104:107]
	ds_read_b128 v[192:195], v173 offset:0
	v_mfma_f32_16x16x32_bf16 v[96:99], v[228:231], v[176:179], v[96:99]
	ds_read_b128 v[196:199], v173 offset:2048
	v_mfma_f32_16x16x32_bf16 v[108:111], v[232:235], v[176:179], v[108:111]
	ds_read_b128 v[200:203], v173 offset:4096
	v_mfma_f32_16x16x32_bf16 v[100:103], v[236:239], v[176:179], v[100:103]
	ds_read_b128 v[204:207], v173 offset:6144
	v_mfma_f32_16x16x32_bf16 v[72:75], v[224:227], v[180:183], v[72:75]
	ds_read_b128 v[208:211], v175 offset:0
	v_mfma_f32_16x16x32_bf16 v[64:67], v[228:231], v[180:183], v[64:67]
	ds_read_b128 v[212:215], v175 offset:2048
	v_mfma_f32_16x16x32_bf16 v[76:79], v[232:235], v[180:183], v[76:79]
	ds_read_b128 v[216:219], v175 offset:4096
	v_mfma_f32_16x16x32_bf16 v[68:71], v[236:239], v[180:183], v[68:71]
	ds_read_b128 v[220:223], v175 offset:6144
	v_mfma_f32_16x16x32_bf16 v[40:43], v[224:227], v[184:187], v[40:43]
	v_mfma_f32_16x16x32_bf16 v[32:35], v[228:231], v[184:187], v[32:35]
	v_mfma_f32_16x16x32_bf16 v[44:47], v[232:235], v[184:187], v[44:47]
	v_mfma_f32_16x16x32_bf16 v[36:39], v[236:239], v[184:187], v[36:39]
	v_mfma_f32_16x16x32_bf16 v[8:11], v[224:227], v[188:191], v[8:11]
	v_mfma_f32_16x16x32_bf16 v[0:3], v[228:231], v[188:191], v[0:3]
	v_mfma_f32_16x16x32_bf16 v[12:15], v[232:235], v[188:191], v[12:15]
	v_mfma_f32_16x16x32_bf16 v[4:7], v[236:239], v[188:191], v[4:7]
	s_waitcnt lgkmcnt(0)
	v_mfma_f32_16x16x32_bf16 v[120:123], v[208:211], v[192:195], v[120:123]
	ds_read_b128 v[224:227], v175 offset:8192
	v_mfma_f32_16x16x32_bf16 v[112:115], v[212:215], v[192:195], v[112:115]
	ds_read_b128 v[228:231], v175 offset:10240
	v_mfma_f32_16x16x32_bf16 v[124:127], v[216:219], v[192:195], v[124:127]
	ds_read_b128 v[232:235], v175 offset:12288
	v_mfma_f32_16x16x32_bf16 v[116:119], v[220:223], v[192:195], v[116:119]
	ds_read_b128 v[236:239], v175 offset:14336
	v_mfma_f32_16x16x32_bf16 v[88:91], v[208:211], v[196:199], v[88:91]
	v_mfma_f32_16x16x32_bf16 v[80:83], v[212:215], v[196:199], v[80:83]
	v_mfma_f32_16x16x32_bf16 v[92:95], v[216:219], v[196:199], v[92:95]
	v_mfma_f32_16x16x32_bf16 v[84:87], v[220:223], v[196:199], v[84:87]
	v_mfma_f32_16x16x32_bf16 v[56:59], v[208:211], v[200:203], v[56:59]
	v_mfma_f32_16x16x32_bf16 v[48:51], v[212:215], v[200:203], v[48:51]
	v_mfma_f32_16x16x32_bf16 v[60:63], v[216:219], v[200:203], v[60:63]
	v_mfma_f32_16x16x32_bf16 v[52:55], v[220:223], v[200:203], v[52:55]
	v_mfma_f32_16x16x32_bf16 v[24:27], v[208:211], v[204:207], v[24:27]
	v_mfma_f32_16x16x32_bf16 v[16:19], v[212:215], v[204:207], v[16:19]
	v_mfma_f32_16x16x32_bf16 v[28:31], v[216:219], v[204:207], v[28:31]
	v_mfma_f32_16x16x32_bf16 v[20:23], v[220:223], v[204:207], v[20:23]
	s_waitcnt lgkmcnt(0)
	s_waitcnt vmcnt(0)
	s_barrier
	s_add_i32 s7, s7, -1
	s_cmp_lg_u32 s7, 0
	s_cbranch_scc1 .Lgemm_p2_loop
	v_mfma_f32_16x16x32_bf16 v[104:107], v[224:227], v[192:195], v[104:107]
	ds_read_b128 v[176:179], v172 offset:32768
	v_mfma_f32_16x16x32_bf16 v[96:99], v[228:231], v[192:195], v[96:99]
	ds_read_b128 v[180:183], v172 offset:34816
	v_mfma_f32_16x16x32_bf16 v[108:111], v[232:235], v[192:195], v[108:111]
	ds_read_b128 v[184:187], v172 offset:36864
	v_mfma_f32_16x16x32_bf16 v[100:103], v[236:239], v[192:195], v[100:103]
	ds_read_b128 v[188:191], v172 offset:38912
	v_mfma_f32_16x16x32_bf16 v[72:75], v[224:227], v[196:199], v[72:75]
	ds_read_b128 v[208:211], v174 offset:32768
	v_mfma_f32_16x16x32_bf16 v[64:67], v[228:231], v[196:199], v[64:67]
	ds_read_b128 v[212:215], v174 offset:34816
	v_mfma_f32_16x16x32_bf16 v[76:79], v[232:235], v[196:199], v[76:79]
	ds_read_b128 v[216:219], v174 offset:36864
	v_mfma_f32_16x16x32_bf16 v[68:71], v[236:239], v[196:199], v[68:71]
	ds_read_b128 v[220:223], v174 offset:38912
	v_mfma_f32_16x16x32_bf16 v[40:43], v[224:227], v[200:203], v[40:43]
	v_mfma_f32_16x16x32_bf16 v[32:35], v[228:231], v[200:203], v[32:35]
	v_mfma_f32_16x16x32_bf16 v[44:47], v[232:235], v[200:203], v[44:47]
	v_mfma_f32_16x16x32_bf16 v[36:39], v[236:239], v[200:203], v[36:39]
	v_mfma_f32_16x16x32_bf16 v[8:11], v[224:227], v[204:207], v[8:11]
	v_mfma_f32_16x16x32_bf16 v[0:3], v[228:231], v[204:207], v[0:3]
	v_mfma_f32_16x16x32_bf16 v[12:15], v[232:235], v[204:207], v[12:15]
	v_mfma_f32_16x16x32_bf16 v[4:7], v[236:239], v[204:207], v[4:7]
	s_waitcnt lgkmcnt(0)
	v_mfma_f32_16x16x32_bf16 v[120:123], v[208:211], v[176:179], v[120:123]
	ds_read_b128 v[224:227], v174 offset:40960
	v_mfma_f32_16x16x32_bf16 v[112:115], v[212:215], v[176:179], v[112:115]
	ds_read_b128 v[228:231], v174 offset:43008
	v_mfma_f32_16x16x32_bf16 v[124:127], v[216:219], v[176:179], v[124:127]
	ds_read_b128 v[232:235], v174 offset:45056
	v_mfma_f32_16x16x32_bf16 v[116:119], v[220:223], v[176:179], v[116:119]
	ds_read_b128 v[236:239], v174 offset:47104
	v_mfma_f32_16x16x32_bf16 v[88:91], v[208:211], v[180:183], v[88:91]
	v_mfma_f32_16x16x32_bf16 v[80:83], v[212:215], v[180:183], v[80:83]
	v_mfma_f32_16x16x32_bf16 v[92:95], v[216:219], v[180:183], v[92:95]
	v_mfma_f32_16x16x32_bf16 v[84:87], v[220:223], v[180:183], v[84:87]
	v_mfma_f32_16x16x32_bf16 v[56:59], v[208:211], v[184:187], v[56:59]
	v_mfma_f32_16x16x32_bf16 v[48:51], v[212:215], v[184:187], v[48:51]
	v_mfma_f32_16x16x32_bf16 v[60:63], v[216:219], v[184:187], v[60:63]
	v_mfma_f32_16x16x32_bf16 v[52:55], v[220:223], v[184:187], v[52:55]
	v_mfma_f32_16x16x32_bf16 v[24:27], v[208:211], v[188:191], v[24:27]
	v_mfma_f32_16x16x32_bf16 v[16:19], v[212:215], v[188:191], v[16:19]
	v_mfma_f32_16x16x32_bf16 v[28:31], v[216:219], v[188:191], v[28:31]
	v_mfma_f32_16x16x32_bf16 v[20:23], v[220:223], v[188:191], v[20:23]
	s_waitcnt lgkmcnt(0)
	v_mfma_f32_16x16x32_bf16 v[104:107], v[224:227], v[176:179], v[104:107]
	ds_read_b128 v[192:195], v173 offset:32768
	v_mfma_f32_16x16x32_bf16 v[96:99], v[228:231], v[176:179], v[96:99]
	ds_read_b128 v[196:199], v173 offset:34816
	v_mfma_f32_16x16x32_bf16 v[108:111], v[232:235], v[176:179], v[108:111]
	ds_read_b128 v[200:203], v173 offset:36864
	v_mfma_f32_16x16x32_bf16 v[100:103], v[236:239], v[176:179], v[100:103]
	ds_read_b128 v[204:207], v173 offset:38912
	v_mfma_f32_16x16x32_bf16 v[72:75], v[224:227], v[180:183], v[72:75]
	ds_read_b128 v[208:211], v175 offset:32768
	v_mfma_f32_16x16x32_bf16 v[64:67], v[228:231], v[180:183], v[64:67]
	ds_read_b128 v[212:215], v175 offset:34816
	v_mfma_f32_16x16x32_bf16 v[76:79], v[232:235], v[180:183], v[76:79]
	ds_read_b128 v[216:219], v175 offset:36864
	v_mfma_f32_16x16x32_bf16 v[68:71], v[236:239], v[180:183], v[68:71]
	ds_read_b128 v[220:223], v175 offset:38912
	v_mfma_f32_16x16x32_bf16 v[40:43], v[224:227], v[184:187], v[40:43]
	v_mfma_f32_16x16x32_bf16 v[32:35], v[228:231], v[184:187], v[32:35]
	v_mfma_f32_16x16x32_bf16 v[44:47], v[232:235], v[184:187], v[44:47]
	v_mfma_f32_16x16x32_bf16 v[36:39], v[236:239], v[184:187], v[36:39]
	v_mfma_f32_16x16x32_bf16 v[8:11], v[224:227], v[188:191], v[8:11]
	v_mfma_f32_16x16x32_bf16 v[0:3], v[228:231], v[188:191], v[0:3]
	v_mfma_f32_16x16x32_bf16 v[12:15], v[232:235], v[188:191], v[12:15]
	v_mfma_f32_16x16x32_bf16 v[4:7], v[236:239], v[188:191], v[4:7]
	s_waitcnt lgkmcnt(0)
	v_mfma_f32_16x16x32_bf16 v[120:123], v[208:211], v[192:195], v[120:123]
	ds_read_b128 v[224:227], v175 offset:40960
	v_mfma_f32_16x16x32_bf16 v[112:115], v[212:215], v[192:195], v[112:115]
	ds_read_b128 v[228:231], v175 offset:43008
	v_mfma_f32_16x16x32_bf16 v[124:127], v[216:219], v[192:195], v[124:127]
	ds_read_b128 v[232:235], v175 offset:45056
	v_mfma_f32_16x16x32_bf16 v[116:119], v[220:223], v[192:195], v[116:119]
	ds_read_b128 v[236:239], v175 offset:47104
	v_mfma_f32_16x16x32_bf16 v[88:91], v[208:211], v[196:199], v[88:91]
	v_mfma_f32_16x16x32_bf16 v[80:83], v[212:215], v[196:199], v[80:83]
	v_mfma_f32_16x16x32_bf16 v[92:95], v[216:219], v[196:199], v[92:95]
	v_mfma_f32_16x16x32_bf16 v[84:87], v[220:223], v[196:199], v[84:87]
	v_mfma_f32_16x16x32_bf16 v[56:59], v[208:211], v[200:203], v[56:59]
	v_mfma_f32_16x16x32_bf16 v[48:51], v[212:215], v[200:203], v[48:51]
	v_mfma_f32_16x16x32_bf16 v[60:63], v[216:219], v[200:203], v[60:63]
	v_mfma_f32_16x16x32_bf16 v[52:55], v[220:223], v[200:203], v[52:55]
	v_mfma_f32_16x16x32_bf16 v[24:27], v[208:211], v[204:207], v[24:27]
	v_mfma_f32_16x16x32_bf16 v[16:19], v[212:215], v[204:207], v[16:19]
	v_mfma_f32_16x16x32_bf16 v[28:31], v[216:219], v[204:207], v[28:31]
	v_mfma_f32_16x16x32_bf16 v[20:23], v[220:223], v[204:207], v[20:23]
	s_waitcnt lgkmcnt(0)
	v_mfma_f32_16x16x32_bf16 v[104:107], v[224:227], v[192:195], v[104:107]
	v_mfma_f32_16x16x32_bf16 v[96:99], v[228:231], v[192:195], v[96:99]
	v_mfma_f32_16x16x32_bf16 v[108:111], v[232:235], v[192:195], v[108:111]
	v_mfma_f32_16x16x32_bf16 v[100:103], v[236:239], v[192:195], v[100:103]
	v_mfma_f32_16x16x32_bf16 v[72:75], v[224:227], v[196:199], v[72:75]
	v_mfma_f32_16x16x32_bf16 v[64:67], v[228:231], v[196:199], v[64:67]
	v_mfma_f32_16x16x32_bf16 v[76:79], v[232:235], v[196:199], v[76:79]
	v_mfma_f32_16x16x32_bf16 v[68:71], v[236:239], v[196:199], v[68:71]
	v_mfma_f32_16x16x32_bf16 v[40:43], v[224:227], v[200:203], v[40:43]
	v_mfma_f32_16x16x32_bf16 v[32:35], v[228:231], v[200:203], v[32:35]
	v_mfma_f32_16x16x32_bf16 v[44:47], v[232:235], v[200:203], v[44:47]
	v_mfma_f32_16x16x32_bf16 v[36:39], v[236:239], v[200:203], v[36:39]
	v_mfma_f32_16x16x32_bf16 v[8:11], v[224:227], v[204:207], v[8:11]
	v_mfma_f32_16x16x32_bf16 v[0:3], v[228:231], v[204:207], v[0:3]
	v_mfma_f32_16x16x32_bf16 v[12:15], v[232:235], v[204:207], v[12:15]
	v_mfma_f32_16x16x32_bf16 v[4:7], v[236:239], v[204:207], v[4:7]
	s_nop 7
	s_nop 3
	s_branch .LBB0_115

.LBB0_1106:
	v_add_u32_e32 v172, v153, v170
	v_add_u32_e32 v173, v153, v171
	v_add_u32_e32 v174, v169, v170
	v_add_u32_e32 v175, v169, v171
	s_mov_b64 s[100:101], 0x80
	v_lshl_add_u64 v[240:241], v[128:129], 0, s[100:101]
	s_mov_b64 s[100:101], 0x6c080
	v_lshl_add_u64 v[242:243], v[128:129], 0, s[100:101]
	s_mov_b64 s[100:101], 0xd8080
	v_lshl_add_u64 v[244:245], v[128:129], 0, s[100:101]
	s_mov_b64 s[100:101], 0x144080
	v_lshl_add_u64 v[246:247], v[128:129], 0, s[100:101]
	s_mov_b64 s[100:101], 0x80
	v_lshl_add_u64 v[138:139], v[130:131], 0, s[100:101]
	s_mov_b64 s[100:101], 0x20080
	v_lshl_add_u64 v[140:141], v[130:131], 0, s[100:101]
	s_mov_b64 s[100:101], 0x40080
	v_lshl_add_u64 v[250:251], v[130:131], 0, s[100:101]
	s_mov_b64 s[100:101], 0x60080
	v_lshl_add_u64 v[252:253], v[130:131], 0, s[100:101]
	v_readfirstlane_b32 s100, v144
	v_readfirstlane_b32 s101, v145
	s_nop 3
	ds_read_b128 v[176:179], v172 offset:0
	ds_read_b128 v[180:183], v172 offset:2048
	ds_read_b128 v[184:187], v172 offset:4096
	ds_read_b128 v[188:191], v172 offset:6144
	ds_read_b128 v[208:211], v174 offset:0
	ds_read_b128 v[212:215], v174 offset:2048
	ds_read_b128 v[216:219], v174 offset:4096
	ds_read_b128 v[220:223], v174 offset:6144
	s_add_u32 m0, s100, 0x8000
	s_nop 0
	global_load_lds_dwordx4 v[240:241], off
	v_lshl_add_u64 v[240:241], v[240:241], 0, s[34:35]
	s_add_u32 m0, s100, 0xa000
	s_nop 0
	global_load_lds_dwordx4 v[242:243], off
	v_lshl_add_u64 v[242:243], v[242:243], 0, s[34:35]
	s_add_u32 m0, s100, 0xc000
	s_nop 0
	global_load_lds_dwordx4 v[244:245], off
	v_lshl_add_u64 v[244:245], v[244:245], 0, s[34:35]
	s_add_u32 m0, s100, 0xe000
	s_nop 0
	global_load_lds_dwordx4 v[246:247], off
	v_lshl_add_u64 v[246:247], v[246:247], 0, s[34:35]
	s_waitcnt lgkmcnt(0)
	v_mfma_f32_16x16x32_bf16 v[124:127], v[208:211], v[176:179], v[124:127]
	ds_read_b128 v[224:227], v174 offset:8192
	v_mfma_f32_16x16x32_bf16 v[120:123], v[212:215], v[176:179], v[120:123]
	ds_read_b128 v[228:231], v174 offset:10240
	v_mfma_f32_16x16x32_bf16 v[116:119], v[216:219], v[176:179], v[116:119]
	ds_read_b128 v[232:235], v174 offset:12288
	v_mfma_f32_16x16x32_bf16 v[112:115], v[220:223], v[176:179], v[112:115]
	ds_read_b128 v[236:239], v174 offset:14336
	v_mfma_f32_16x16x32_bf16 v[92:95], v[208:211], v[180:183], v[92:95]
	s_add_u32 m0, s101, 0x8000
	v_mfma_f32_16x16x32_bf16 v[88:91], v[212:215], v[180:183], v[88:91]
	global_load_lds_dwordx4 v[138:139], off
	v_lshl_add_u64 v[138:139], v[138:139], 0, s[34:35]
	v_mfma_f32_16x16x32_bf16 v[84:87], v[216:219], v[180:183], v[84:87]
	s_add_u32 m0, s101, 0xa000
	v_mfma_f32_16x16x32_bf16 v[80:83], v[220:223], v[180:183], v[80:83]
	global_load_lds_dwordx4 v[140:141], off
	v_lshl_add_u64 v[140:141], v[140:141], 0, s[34:35]
	v_mfma_f32_16x16x32_bf16 v[60:63], v[208:211], v[184:187], v[60:63]
	s_add_u32 m0, s101, 0xc000
	v_mfma_f32_16x16x32_bf16 v[56:59], v[212:215], v[184:187], v[56:59]
	global_load_lds_dwordx4 v[250:251], off
	v_lshl_add_u64 v[250:251], v[250:251], 0, s[34:35]
	v_mfma_f32_16x16x32_bf16 v[52:55], v[216:219], v[184:187], v[52:55]
	s_add_u32 m0, s101, 0xe000
	v_mfma_f32_16x16x32_bf16 v[48:51], v[220:223], v[184:187], v[48:51]
	global_load_lds_dwordx4 v[252:253], off
	v_lshl_add_u64 v[252:253], v[252:253], 0, s[34:35]
	v_mfma_f32_16x16x32_bf16 v[28:31], v[208:211], v[188:191], v[28:31]
	v_mfma_f32_16x16x32_bf16 v[24:27], v[212:215], v[188:191], v[24:27]
	v_mfma_f32_16x16x32_bf16 v[20:23], v[216:219], v[188:191], v[20:23]
	v_mfma_f32_16x16x32_bf16 v[16:19], v[220:223], v[188:191], v[16:19]
	s_waitcnt lgkmcnt(0)
	v_mfma_f32_16x16x32_bf16 v[108:111], v[224:227], v[176:179], v[108:111]
	ds_read_b128 v[192:195], v173 offset:0
	v_mfma_f32_16x16x32_bf16 v[104:107], v[228:231], v[176:179], v[104:107]
	ds_read_b128 v[196:199], v173 offset:2048
	v_mfma_f32_16x16x32_bf16 v[100:103], v[232:235], v[176:179], v[100:103]
	ds_read_b128 v[200:203], v173 offset:4096
	v_mfma_f32_16x16x32_bf16 v[96:99], v[236:239], v[176:179], v[96:99]
	ds_read_b128 v[204:207], v173 offset:6144
	v_mfma_f32_16x16x32_bf16 v[76:79], v[224:227], v[180:183], v[76:79]
	ds_read_b128 v[208:211], v175 offset:0
	v_mfma_f32_16x16x32_bf16 v[72:75], v[228:231], v[180:183], v[72:75]
	ds_read_b128 v[212:215], v175 offset:2048
	v_mfma_f32_16x16x32_bf16 v[68:71], v[232:235], v[180:183], v[68:71]
	ds_read_b128 v[216:219], v175 offset:4096
	v_mfma_f32_16x16x32_bf16 v[64:67], v[236:239], v[180:183], v[64:67]
	ds_read_b128 v[220:223], v175 offset:6144
	v_mfma_f32_16x16x32_bf16 v[44:47], v[224:227], v[184:187], v[44:47]
	v_mfma_f32_16x16x32_bf16 v[40:43], v[228:231], v[184:187], v[40:43]
	v_mfma_f32_16x16x32_bf16 v[36:39], v[232:235], v[184:187], v[36:39]
	v_mfma_f32_16x16x32_bf16 v[32:35], v[236:239], v[184:187], v[32:35]
	v_mfma_f32_16x16x32_bf16 v[12:15], v[224:227], v[188:191], v[12:15]
	v_mfma_f32_16x16x32_bf16 v[8:11], v[228:231], v[188:191], v[8:11]
	v_mfma_f32_16x16x32_bf16 v[4:7], v[232:235], v[188:191], v[4:7]
	v_mfma_f32_16x16x32_bf16 v[0:3], v[236:239], v[188:191], v[0:3]
	s_waitcnt lgkmcnt(0)
	v_mfma_f32_16x16x32_bf16 v[124:127], v[208:211], v[192:195], v[124:127]
	ds_read_b128 v[224:227], v175 offset:8192
	v_mfma_f32_16x16x32_bf16 v[120:123], v[212:215], v[192:195], v[120:123]
	ds_read_b128 v[228:231], v175 offset:10240
	v_mfma_f32_16x16x32_bf16 v[116:119], v[216:219], v[192:195], v[116:119]
	ds_read_b128 v[232:235], v175 offset:12288
	v_mfma_f32_16x16x32_bf16 v[112:115], v[220:223], v[192:195], v[112:115]
	ds_read_b128 v[236:239], v175 offset:14336
	v_mfma_f32_16x16x32_bf16 v[92:95], v[208:211], v[196:199], v[92:95]
	v_mfma_f32_16x16x32_bf16 v[88:91], v[212:215], v[196:199], v[88:91]
	v_mfma_f32_16x16x32_bf16 v[84:87], v[216:219], v[196:199], v[84:87]
	v_mfma_f32_16x16x32_bf16 v[80:83], v[220:223], v[196:199], v[80:83]
	v_mfma_f32_16x16x32_bf16 v[60:63], v[208:211], v[200:203], v[60:63]
	v_mfma_f32_16x16x32_bf16 v[56:59], v[212:215], v[200:203], v[56:59]
	v_mfma_f32_16x16x32_bf16 v[52:55], v[216:219], v[200:203], v[52:55]
	v_mfma_f32_16x16x32_bf16 v[48:51], v[220:223], v[200:203], v[48:51]
	v_mfma_f32_16x16x32_bf16 v[28:31], v[208:211], v[204:207], v[28:31]
	v_mfma_f32_16x16x32_bf16 v[24:27], v[212:215], v[204:207], v[24:27]
	v_mfma_f32_16x16x32_bf16 v[20:23], v[216:219], v[204:207], v[20:23]
	v_mfma_f32_16x16x32_bf16 v[16:19], v[220:223], v[204:207], v[16:19]
	s_waitcnt lgkmcnt(0)
	s_waitcnt vmcnt(0)
	s_barrier
	s_mov_b32 s46, 7
.Lgemm_p7_loop:
	v_mfma_f32_16x16x32_bf16 v[108:111], v[224:227], v[192:195], v[108:111]
	ds_read_b128 v[176:179], v172 offset:32768
	v_mfma_f32_16x16x32_bf16 v[104:107], v[228:231], v[192:195], v[104:107]
	ds_read_b128 v[180:183], v172 offset:34816
	v_mfma_f32_16x16x32_bf16 v[100:103], v[232:235], v[192:195], v[100:103]
	ds_read_b128 v[184:187], v172 offset:36864
	v_mfma_f32_16x16x32_bf16 v[96:99], v[236:239], v[192:195], v[96:99]
	ds_read_b128 v[188:191], v172 offset:38912
	v_mfma_f32_16x16x32_bf16 v[76:79], v[224:227], v[196:199], v[76:79]
	ds_read_b128 v[208:211], v174 offset:32768
	v_mfma_f32_16x16x32_bf16 v[72:75], v[228:231], v[196:199], v[72:75]
	ds_read_b128 v[212:215], v174 offset:34816
	v_mfma_f32_16x16x32_bf16 v[68:71], v[232:235], v[196:199], v[68:71]
	ds_read_b128 v[216:219], v174 offset:36864
	v_mfma_f32_16x16x32_bf16 v[64:67], v[236:239], v[196:199], v[64:67]
	ds_read_b128 v[220:223], v174 offset:38912
	v_mfma_f32_16x16x32_bf16 v[44:47], v[224:227], v[200:203], v[44:47]
	s_mov_b32 m0, s100
	v_mfma_f32_16x16x32_bf16 v[40:43], v[228:231], v[200:203], v[40:43]
	global_load_lds_dwordx4 v[240:241], off
	v_lshl_add_u64 v[240:241], v[240:241], 0, s[34:35]
	v_mfma_f32_16x16x32_bf16 v[36:39], v[232:235], v[200:203], v[36:39]
	s_add_u32 m0, s100, 0x2000
	v_mfma_f32_16x16x32_bf16 v[32:35], v[236:239], v[200:203], v[32:35]
	global_load_lds_dwordx4 v[242:243], off
	v_lshl_add_u64 v[242:243], v[242:243], 0, s[34:35]
	v_mfma_f32_16x16x32_bf16 v[12:15], v[224:227], v[204:207], v[12:15]
	s_add_u32 m0, s100, 0x4000
	v_mfma_f32_16x16x32_bf16 v[8:11], v[228:231], v[204:207], v[8:11]
	global_load_lds_dwordx4 v[244:245], off
	v_lshl_add_u64 v[244:245], v[244:245], 0, s[34:35]
	v_mfma_f32_16x16x32_bf16 v[4:7], v[232:235], v[204:207], v[4:7]
	s_add_u32 m0, s100, 0x6000
	v_mfma_f32_16x16x32_bf16 v[0:3], v[236:239], v[204:207], v[0:3]
	global_load_lds_dwordx4 v[246:247], off
	v_lshl_add_u64 v[246:247], v[246:247], 0, s[34:35]
	s_waitcnt lgkmcnt(0)
	v_mfma_f32_16x16x32_bf16 v[124:127], v[208:211], v[176:179], v[124:127]
	ds_read_b128 v[224:227], v174 offset:40960
	v_mfma_f32_16x16x32_bf16 v[120:123], v[212:215], v[176:179], v[120:123]
	ds_read_b128 v[228:231], v174 offset:43008
	v_mfma_f32_16x16x32_bf16 v[116:119], v[216:219], v[176:179], v[116:119]
	ds_read_b128 v[232:235], v174 offset:45056
	v_mfma_f32_16x16x32_bf16 v[112:115], v[220:223], v[176:179], v[112:115]
	ds_read_b128 v[236:239], v174 offset:47104
	v_mfma_f32_16x16x32_bf16 v[92:95], v[208:211], v[180:183], v[92:95]
	s_mov_b32 m0, s101
	v_mfma_f32_16x16x32_bf16 v[88:91], v[212:215], v[180:183], v[88:91]
	global_load_lds_dwordx4 v[138:139], off
	v_lshl_add_u64 v[138:139], v[138:139], 0, s[34:35]
	v_mfma_f32_16x16x32_bf16 v[84:87], v[216:219], v[180:183], v[84:87]
	s_add_u32 m0, s101, 0x2000
	v_mfma_f32_16x16x32_bf16 v[80:83], v[220:223], v[180:183], v[80:83]
	global_load_lds_dwordx4 v[140:141], off
	v_lshl_add_u64 v[140:141], v[140:141], 0, s[34:35]
	v_mfma_f32_16x16x32_bf16 v[60:63], v[208:211], v[184:187], v[60:63]
	s_add_u32 m0, s101, 0x4000
	v_mfma_f32_16x16x32_bf16 v[56:59], v[212:215], v[184:187], v[56:59]
	global_load_lds_dwordx4 v[250:251], off
	v_lshl_add_u64 v[250:251], v[250:251], 0, s[34:35]
	v_mfma_f32_16x16x32_bf16 v[52:55], v[216:219], v[184:187], v[52:55]
	s_add_u32 m0, s101, 0x6000
	v_mfma_f32_16x16x32_bf16 v[48:51], v[220:223], v[184:187], v[48:51]
	global_load_lds_dwordx4 v[252:253], off
	v_lshl_add_u64 v[252:253], v[252:253], 0, s[34:35]
	v_mfma_f32_16x16x32_bf16 v[28:31], v[208:211], v[188:191], v[28:31]
	v_mfma_f32_16x16x32_bf16 v[24:27], v[212:215], v[188:191], v[24:27]
	v_mfma_f32_16x16x32_bf16 v[20:23], v[216:219], v[188:191], v[20:23]
	v_mfma_f32_16x16x32_bf16 v[16:19], v[220:223], v[188:191], v[16:19]
	s_waitcnt lgkmcnt(0)
	v_mfma_f32_16x16x32_bf16 v[108:111], v[224:227], v[176:179], v[108:111]
	ds_read_b128 v[192:195], v173 offset:32768
	v_mfma_f32_16x16x32_bf16 v[104:107], v[228:231], v[176:179], v[104:107]
	ds_read_b128 v[196:199], v173 offset:34816
	v_mfma_f32_16x16x32_bf16 v[100:103], v[232:235], v[176:179], v[100:103]
	ds_read_b128 v[200:203], v173 offset:36864
	v_mfma_f32_16x16x32_bf16 v[96:99], v[236:239], v[176:179], v[96:99]
	ds_read_b128 v[204:207], v173 offset:38912
	v_mfma_f32_16x16x32_bf16 v[76:79], v[224:227], v[180:183], v[76:79]
	ds_read_b128 v[208:211], v175 offset:32768
	v_mfma_f32_16x16x32_bf16 v[72:75], v[228:231], v[180:183], v[72:75]
	ds_read_b128 v[212:215], v175 offset:34816
	v_mfma_f32_16x16x32_bf16 v[68:71], v[232:235], v[180:183], v[68:71]
	ds_read_b128 v[216:219], v175 offset:36864
	v_mfma_f32_16x16x32_bf16 v[64:67], v[236:239], v[180:183], v[64:67]
	ds_read_b128 v[220:223], v175 offset:38912
	v_mfma_f32_16x16x32_bf16 v[44:47], v[224:227], v[184:187], v[44:47]
	v_mfma_f32_16x16x32_bf16 v[40:43], v[228:231], v[184:187], v[40:43]
	v_mfma_f32_16x16x32_bf16 v[36:39], v[232:235], v[184:187], v[36:39]
	v_mfma_f32_16x16x32_bf16 v[32:35], v[236:239], v[184:187], v[32:35]
	v_mfma_f32_16x16x32_bf16 v[12:15], v[224:227], v[188:191], v[12:15]
	v_mfma_f32_16x16x32_bf16 v[8:11], v[228:231], v[188:191], v[8:11]
	v_mfma_f32_16x16x32_bf16 v[4:7], v[232:235], v[188:191], v[4:7]
	v_mfma_f32_16x16x32_bf16 v[0:3], v[236:239], v[188:191], v[0:3]
	s_waitcnt lgkmcnt(0)
	v_mfma_f32_16x16x32_bf16 v[124:127], v[208:211], v[192:195], v[124:127]
	ds_read_b128 v[224:227], v175 offset:40960
	v_mfma_f32_16x16x32_bf16 v[120:123], v[212:215], v[192:195], v[120:123]
	ds_read_b128 v[228:231], v175 offset:43008
	v_mfma_f32_16x16x32_bf16 v[116:119], v[216:219], v[192:195], v[116:119]
	ds_read_b128 v[232:235], v175 offset:45056
	v_mfma_f32_16x16x32_bf16 v[112:115], v[220:223], v[192:195], v[112:115]
	ds_read_b128 v[236:239], v175 offset:47104
	v_mfma_f32_16x16x32_bf16 v[92:95], v[208:211], v[196:199], v[92:95]
	v_mfma_f32_16x16x32_bf16 v[88:91], v[212:215], v[196:199], v[88:91]
	v_mfma_f32_16x16x32_bf16 v[84:87], v[216:219], v[196:199], v[84:87]
	v_mfma_f32_16x16x32_bf16 v[80:83], v[220:223], v[196:199], v[80:83]
	v_mfma_f32_16x16x32_bf16 v[60:63], v[208:211], v[200:203], v[60:63]
	v_mfma_f32_16x16x32_bf16 v[56:59], v[212:215], v[200:203], v[56:59]
	v_mfma_f32_16x16x32_bf16 v[52:55], v[216:219], v[200:203], v[52:55]
	v_mfma_f32_16x16x32_bf16 v[48:51], v[220:223], v[200:203], v[48:51]
	v_mfma_f32_16x16x32_bf16 v[28:31], v[208:211], v[204:207], v[28:31]
	v_mfma_f32_16x16x32_bf16 v[24:27], v[212:215], v[204:207], v[24:27]
	v_mfma_f32_16x16x32_bf16 v[20:23], v[216:219], v[204:207], v[20:23]
	v_mfma_f32_16x16x32_bf16 v[16:19], v[220:223], v[204:207], v[16:19]
	s_waitcnt lgkmcnt(0)
	s_waitcnt vmcnt(0)
	s_barrier
	v_mfma_f32_16x16x32_bf16 v[108:111], v[224:227], v[192:195], v[108:111]
	ds_read_b128 v[176:179], v172 offset:0
	v_mfma_f32_16x16x32_bf16 v[104:107], v[228:231], v[192:195], v[104:107]
	ds_read_b128 v[180:183], v172 offset:2048
	v_mfma_f32_16x16x32_bf16 v[100:103], v[232:235], v[192:195], v[100:103]
	ds_read_b128 v[184:187], v172 offset:4096
	v_mfma_f32_16x16x32_bf16 v[96:99], v[236:239], v[192:195], v[96:99]
	ds_read_b128 v[188:191], v172 offset:6144
	v_mfma_f32_16x16x32_bf16 v[76:79], v[224:227], v[196:199], v[76:79]
	ds_read_b128 v[208:211], v174 offset:0
	v_mfma_f32_16x16x32_bf16 v[72:75], v[228:231], v[196:199], v[72:75]
	ds_read_b128 v[212:215], v174 offset:2048
	v_mfma_f32_16x16x32_bf16 v[68:71], v[232:235], v[196:199], v[68:71]
	ds_read_b128 v[216:219], v174 offset:4096
	v_mfma_f32_16x16x32_bf16 v[64:67], v[236:239], v[196:199], v[64:67]
	ds_read_b128 v[220:223], v174 offset:6144
	v_mfma_f32_16x16x32_bf16 v[44:47], v[224:227], v[200:203], v[44:47]
	s_add_u32 m0, s100, 0x8000
	v_mfma_f32_16x16x32_bf16 v[40:43], v[228:231], v[200:203], v[40:43]
	global_load_lds_dwordx4 v[240:241], off
	v_lshl_add_u64 v[240:241], v[240:241], 0, s[34:35]
	v_mfma_f32_16x16x32_bf16 v[36:39], v[232:235], v[200:203], v[36:39]
	s_add_u32 m0, s100, 0xa000
	v_mfma_f32_16x16x32_bf16 v[32:35], v[236:239], v[200:203], v[32:35]
	global_load_lds_dwordx4 v[242:243], off
	v_lshl_add_u64 v[242:243], v[242:243], 0, s[34:35]
	v_mfma_f32_16x16x32_bf16 v[12:15], v[224:227], v[204:207], v[12:15]
	s_add_u32 m0, s100, 0xc000
	v_mfma_f32_16x16x32_bf16 v[8:11], v[228:231], v[204:207], v[8:11]
	global_load_lds_dwordx4 v[244:245], off
	v_lshl_add_u64 v[244:245], v[244:245], 0, s[34:35]
	v_mfma_f32_16x16x32_bf16 v[4:7], v[232:235], v[204:207], v[4:7]
	s_add_u32 m0, s100, 0xe000
	v_mfma_f32_16x16x32_bf16 v[0:3], v[236:239], v[204:207], v[0:3]
	global_load_lds_dwordx4 v[246:247], off
	v_lshl_add_u64 v[246:247], v[246:247], 0, s[34:35]
	s_waitcnt lgkmcnt(0)
	v_mfma_f32_16x16x32_bf16 v[124:127], v[208:211], v[176:179], v[124:127]
	ds_read_b128 v[224:227], v174 offset:8192
	v_mfma_f32_16x16x32_bf16 v[120:123], v[212:215], v[176:179], v[120:123]
	ds_read_b128 v[228:231], v174 offset:10240
	v_mfma_f32_16x16x32_bf16 v[116:119], v[216:219], v[176:179], v[116:119]
	ds_read_b128 v[232:235], v174 offset:12288
	v_mfma_f32_16x16x32_bf16 v[112:115], v[220:223], v[176:179], v[112:115]
	ds_read_b128 v[236:239], v174 offset:14336
	v_mfma_f32_16x16x32_bf16 v[92:95], v[208:211], v[180:183], v[92:95]
	s_add_u32 m0, s101, 0x8000
	v_mfma_f32_16x16x32_bf16 v[88:91], v[212:215], v[180:183], v[88:91]
	global_load_lds_dwordx4 v[138:139], off
	v_lshl_add_u64 v[138:139], v[138:139], 0, s[34:35]
	v_mfma_f32_16x16x32_bf16 v[84:87], v[216:219], v[180:183], v[84:87]
	s_add_u32 m0, s101, 0xa000
	v_mfma_f32_16x16x32_bf16 v[80:83], v[220:223], v[180:183], v[80:83]
	global_load_lds_dwordx4 v[140:141], off
	v_lshl_add_u64 v[140:141], v[140:141], 0, s[34:35]
	v_mfma_f32_16x16x32_bf16 v[60:63], v[208:211], v[184:187], v[60:63]
	s_add_u32 m0, s101, 0xc000
	v_mfma_f32_16x16x32_bf16 v[56:59], v[212:215], v[184:187], v[56:59]
	global_load_lds_dwordx4 v[250:251], off
	v_lshl_add_u64 v[250:251], v[250:251], 0, s[34:35]
	v_mfma_f32_16x16x32_bf16 v[52:55], v[216:219], v[184:187], v[52:55]
	s_add_u32 m0, s101, 0xe000
	v_mfma_f32_16x16x32_bf16 v[48:51], v[220:223], v[184:187], v[48:51]
	global_load_lds_dwordx4 v[252:253], off
	v_lshl_add_u64 v[252:253], v[252:253], 0, s[34:35]
	v_mfma_f32_16x16x32_bf16 v[28:31], v[208:211], v[188:191], v[28:31]
	v_mfma_f32_16x16x32_bf16 v[24:27], v[212:215], v[188:191], v[24:27]
	v_mfma_f32_16x16x32_bf16 v[20:23], v[216:219], v[188:191], v[20:23]
	v_mfma_f32_16x16x32_bf16 v[16:19], v[220:223], v[188:191], v[16:19]
	s_waitcnt lgkmcnt(0)
	v_mfma_f32_16x16x32_bf16 v[108:111], v[224:227], v[176:179], v[108:111]
	ds_read_b128 v[192:195], v173 offset:0
	v_mfma_f32_16x16x32_bf16 v[104:107], v[228:231], v[176:179], v[104:107]
	ds_read_b128 v[196:199], v173 offset:2048
	v_mfma_f32_16x16x32_bf16 v[100:103], v[232:235], v[176:179], v[100:103]
	ds_read_b128 v[200:203], v173 offset:4096
	v_mfma_f32_16x16x32_bf16 v[96:99], v[236:239], v[176:179], v[96:99]
	ds_read_b128 v[204:207], v173 offset:6144
	v_mfma_f32_16x16x32_bf16 v[76:79], v[224:227], v[180:183], v[76:79]
	ds_read_b128 v[208:211], v175 offset:0
	v_mfma_f32_16x16x32_bf16 v[72:75], v[228:231], v[180:183], v[72:75]
	ds_read_b128 v[212:215], v175 offset:2048
	v_mfma_f32_16x16x32_bf16 v[68:71], v[232:235], v[180:183], v[68:71]
	ds_read_b128 v[216:219], v175 offset:4096
	v_mfma_f32_16x16x32_bf16 v[64:67], v[236:239], v[180:183], v[64:67]
	ds_read_b128 v[220:223], v175 offset:6144
	v_mfma_f32_16x16x32_bf16 v[44:47], v[224:227], v[184:187], v[44:47]
	v_mfma_f32_16x16x32_bf16 v[40:43], v[228:231], v[184:187], v[40:43]
	v_mfma_f32_16x16x32_bf16 v[36:39], v[232:235], v[184:187], v[36:39]
	v_mfma_f32_16x16x32_bf16 v[32:35], v[236:239], v[184:187], v[32:35]
	v_mfma_f32_16x16x32_bf16 v[12:15], v[224:227], v[188:191], v[12:15]
	v_mfma_f32_16x16x32_bf16 v[8:11], v[228:231], v[188:191], v[8:11]
	v_mfma_f32_16x16x32_bf16 v[4:7], v[232:235], v[188:191], v[4:7]
	v_mfma_f32_16x16x32_bf16 v[0:3], v[236:239], v[188:191], v[0:3]
	s_waitcnt lgkmcnt(0)
	v_mfma_f32_16x16x32_bf16 v[124:127], v[208:211], v[192:195], v[124:127]
	ds_read_b128 v[224:227], v175 offset:8192
	v_mfma_f32_16x16x32_bf16 v[120:123], v[212:215], v[192:195], v[120:123]
	ds_read_b128 v[228:231], v175 offset:10240
	v_mfma_f32_16x16x32_bf16 v[116:119], v[216:219], v[192:195], v[116:119]
	ds_read_b128 v[232:235], v175 offset:12288
	v_mfma_f32_16x16x32_bf16 v[112:115], v[220:223], v[192:195], v[112:115]
	ds_read_b128 v[236:239], v175 offset:14336
	v_mfma_f32_16x16x32_bf16 v[92:95], v[208:211], v[196:199], v[92:95]
	v_mfma_f32_16x16x32_bf16 v[88:91], v[212:215], v[196:199], v[88:91]
	v_mfma_f32_16x16x32_bf16 v[84:87], v[216:219], v[196:199], v[84:87]
	v_mfma_f32_16x16x32_bf16 v[80:83], v[220:223], v[196:199], v[80:83]
	v_mfma_f32_16x16x32_bf16 v[60:63], v[208:211], v[200:203], v[60:63]
	v_mfma_f32_16x16x32_bf16 v[56:59], v[212:215], v[200:203], v[56:59]
	v_mfma_f32_16x16x32_bf16 v[52:55], v[216:219], v[200:203], v[52:55]
	v_mfma_f32_16x16x32_bf16 v[48:51], v[220:223], v[200:203], v[48:51]
	v_mfma_f32_16x16x32_bf16 v[28:31], v[208:211], v[204:207], v[28:31]
	v_mfma_f32_16x16x32_bf16 v[24:27], v[212:215], v[204:207], v[24:27]
	v_mfma_f32_16x16x32_bf16 v[20:23], v[216:219], v[204:207], v[20:23]
	v_mfma_f32_16x16x32_bf16 v[16:19], v[220:223], v[204:207], v[16:19]
	s_waitcnt lgkmcnt(0)
	s_waitcnt vmcnt(0)
	s_barrier
	s_add_i32 s46, s46, -1
	s_cmp_lg_u32 s46, 0
	s_cbranch_scc1 .Lgemm_p7_loop
	v_mfma_f32_16x16x32_bf16 v[108:111], v[224:227], v[192:195], v[108:111]
	ds_read_b128 v[176:179], v172 offset:32768
	v_mfma_f32_16x16x32_bf16 v[104:107], v[228:231], v[192:195], v[104:107]
	ds_read_b128 v[180:183], v172 offset:34816
	v_mfma_f32_16x16x32_bf16 v[100:103], v[232:235], v[192:195], v[100:103]
	ds_read_b128 v[184:187], v172 offset:36864
	v_mfma_f32_16x16x32_bf16 v[96:99], v[236:239], v[192:195], v[96:99]
	ds_read_b128 v[188:191], v172 offset:38912
	v_mfma_f32_16x16x32_bf16 v[76:79], v[224:227], v[196:199], v[76:79]
	ds_read_b128 v[208:211], v174 offset:32768
	v_mfma_f32_16x16x32_bf16 v[72:75], v[228:231], v[196:199], v[72:75]
	ds_read_b128 v[212:215], v174 offset:34816
	v_mfma_f32_16x16x32_bf16 v[68:71], v[232:235], v[196:199], v[68:71]
	ds_read_b128 v[216:219], v174 offset:36864
	v_mfma_f32_16x16x32_bf16 v[64:67], v[236:239], v[196:199], v[64:67]
	ds_read_b128 v[220:223], v174 offset:38912
	v_mfma_f32_16x16x32_bf16 v[44:47], v[224:227], v[200:203], v[44:47]
	v_mfma_f32_16x16x32_bf16 v[40:43], v[228:231], v[200:203], v[40:43]
	v_mfma_f32_16x16x32_bf16 v[36:39], v[232:235], v[200:203], v[36:39]
	v_mfma_f32_16x16x32_bf16 v[32:35], v[236:239], v[200:203], v[32:35]
	v_mfma_f32_16x16x32_bf16 v[12:15], v[224:227], v[204:207], v[12:15]
	v_mfma_f32_16x16x32_bf16 v[8:11], v[228:231], v[204:207], v[8:11]
	v_mfma_f32_16x16x32_bf16 v[4:7], v[232:235], v[204:207], v[4:7]
	v_mfma_f32_16x16x32_bf16 v[0:3], v[236:239], v[204:207], v[0:3]
	s_waitcnt lgkmcnt(0)
	v_mfma_f32_16x16x32_bf16 v[124:127], v[208:211], v[176:179], v[124:127]
	ds_read_b128 v[224:227], v174 offset:40960
	v_mfma_f32_16x16x32_bf16 v[120:123], v[212:215], v[176:179], v[120:123]
	ds_read_b128 v[228:231], v174 offset:43008
	v_mfma_f32_16x16x32_bf16 v[116:119], v[216:219], v[176:179], v[116:119]
	ds_read_b128 v[232:235], v174 offset:45056
	v_mfma_f32_16x16x32_bf16 v[112:115], v[220:223], v[176:179], v[112:115]
	ds_read_b128 v[236:239], v174 offset:47104
	v_mfma_f32_16x16x32_bf16 v[92:95], v[208:211], v[180:183], v[92:95]
	v_mfma_f32_16x16x32_bf16 v[88:91], v[212:215], v[180:183], v[88:91]
	v_mfma_f32_16x16x32_bf16 v[84:87], v[216:219], v[180:183], v[84:87]
	v_mfma_f32_16x16x32_bf16 v[80:83], v[220:223], v[180:183], v[80:83]
	v_mfma_f32_16x16x32_bf16 v[60:63], v[208:211], v[184:187], v[60:63]
	v_mfma_f32_16x16x32_bf16 v[56:59], v[212:215], v[184:187], v[56:59]
	v_mfma_f32_16x16x32_bf16 v[52:55], v[216:219], v[184:187], v[52:55]
	v_mfma_f32_16x16x32_bf16 v[48:51], v[220:223], v[184:187], v[48:51]
	v_mfma_f32_16x16x32_bf16 v[28:31], v[208:211], v[188:191], v[28:31]
	v_mfma_f32_16x16x32_bf16 v[24:27], v[212:215], v[188:191], v[24:27]
	v_mfma_f32_16x16x32_bf16 v[20:23], v[216:219], v[188:191], v[20:23]
	v_mfma_f32_16x16x32_bf16 v[16:19], v[220:223], v[188:191], v[16:19]
	s_waitcnt lgkmcnt(0)
	v_mfma_f32_16x16x32_bf16 v[108:111], v[224:227], v[176:179], v[108:111]
	ds_read_b128 v[192:195], v173 offset:32768
	v_mfma_f32_16x16x32_bf16 v[104:107], v[228:231], v[176:179], v[104:107]
	ds_read_b128 v[196:199], v173 offset:34816
	v_mfma_f32_16x16x32_bf16 v[100:103], v[232:235], v[176:179], v[100:103]
	ds_read_b128 v[200:203], v173 offset:36864
	v_mfma_f32_16x16x32_bf16 v[96:99], v[236:239], v[176:179], v[96:99]
	ds_read_b128 v[204:207], v173 offset:38912
	v_mfma_f32_16x16x32_bf16 v[76:79], v[224:227], v[180:183], v[76:79]
	ds_read_b128 v[208:211], v175 offset:32768
	v_mfma_f32_16x16x32_bf16 v[72:75], v[228:231], v[180:183], v[72:75]
	ds_read_b128 v[212:215], v175 offset:34816
	v_mfma_f32_16x16x32_bf16 v[68:71], v[232:235], v[180:183], v[68:71]
	ds_read_b128 v[216:219], v175 offset:36864
	v_mfma_f32_16x16x32_bf16 v[64:67], v[236:239], v[180:183], v[64:67]
	ds_read_b128 v[220:223], v175 offset:38912
	v_mfma_f32_16x16x32_bf16 v[44:47], v[224:227], v[184:187], v[44:47]
	v_mfma_f32_16x16x32_bf16 v[40:43], v[228:231], v[184:187], v[40:43]
	v_mfma_f32_16x16x32_bf16 v[36:39], v[232:235], v[184:187], v[36:39]
	v_mfma_f32_16x16x32_bf16 v[32:35], v[236:239], v[184:187], v[32:35]
	v_mfma_f32_16x16x32_bf16 v[12:15], v[224:227], v[188:191], v[12:15]
	v_mfma_f32_16x16x32_bf16 v[8:11], v[228:231], v[188:191], v[8:11]
	v_mfma_f32_16x16x32_bf16 v[4:7], v[232:235], v[188:191], v[4:7]
	v_mfma_f32_16x16x32_bf16 v[0:3], v[236:239], v[188:191], v[0:3]
	s_waitcnt lgkmcnt(0)
	v_mfma_f32_16x16x32_bf16 v[124:127], v[208:211], v[192:195], v[124:127]
	ds_read_b128 v[224:227], v175 offset:40960
	v_mfma_f32_16x16x32_bf16 v[120:123], v[212:215], v[192:195], v[120:123]
	ds_read_b128 v[228:231], v175 offset:43008
	v_mfma_f32_16x16x32_bf16 v[116:119], v[216:219], v[192:195], v[116:119]
	ds_read_b128 v[232:235], v175 offset:45056
	v_mfma_f32_16x16x32_bf16 v[112:115], v[220:223], v[192:195], v[112:115]
	ds_read_b128 v[236:239], v175 offset:47104
	v_mfma_f32_16x16x32_bf16 v[92:95], v[208:211], v[196:199], v[92:95]
	v_mfma_f32_16x16x32_bf16 v[88:91], v[212:215], v[196:199], v[88:91]
	v_mfma_f32_16x16x32_bf16 v[84:87], v[216:219], v[196:199], v[84:87]
	v_mfma_f32_16x16x32_bf16 v[80:83], v[220:223], v[196:199], v[80:83]
	v_mfma_f32_16x16x32_bf16 v[60:63], v[208:211], v[200:203], v[60:63]
	v_mfma_f32_16x16x32_bf16 v[56:59], v[212:215], v[200:203], v[56:59]
	v_mfma_f32_16x16x32_bf16 v[52:55], v[216:219], v[200:203], v[52:55]
	v_mfma_f32_16x16x32_bf16 v[48:51], v[220:223], v[200:203], v[48:51]
	v_mfma_f32_16x16x32_bf16 v[28:31], v[208:211], v[204:207], v[28:31]
	v_mfma_f32_16x16x32_bf16 v[24:27], v[212:215], v[204:207], v[24:27]
	v_mfma_f32_16x16x32_bf16 v[20:23], v[216:219], v[204:207], v[20:23]
	v_mfma_f32_16x16x32_bf16 v[16:19], v[220:223], v[204:207], v[16:19]
	s_waitcnt lgkmcnt(0)
	v_mfma_f32_16x16x32_bf16 v[108:111], v[224:227], v[192:195], v[108:111]
	v_mfma_f32_16x16x32_bf16 v[104:107], v[228:231], v[192:195], v[104:107]
	v_mfma_f32_16x16x32_bf16 v[100:103], v[232:235], v[192:195], v[100:103]
	v_mfma_f32_16x16x32_bf16 v[96:99], v[236:239], v[192:195], v[96:99]
	v_mfma_f32_16x16x32_bf16 v[76:79], v[224:227], v[196:199], v[76:79]
	v_mfma_f32_16x16x32_bf16 v[72:75], v[228:231], v[196:199], v[72:75]
	v_mfma_f32_16x16x32_bf16 v[68:71], v[232:235], v[196:199], v[68:71]
	v_mfma_f32_16x16x32_bf16 v[64:67], v[236:239], v[196:199], v[64:67]
	v_mfma_f32_16x16x32_bf16 v[44:47], v[224:227], v[200:203], v[44:47]
	v_mfma_f32_16x16x32_bf16 v[40:43], v[228:231], v[200:203], v[40:43]
	v_mfma_f32_16x16x32_bf16 v[36:39], v[232:235], v[200:203], v[36:39]
	v_mfma_f32_16x16x32_bf16 v[32:35], v[236:239], v[200:203], v[32:35]
	v_mfma_f32_16x16x32_bf16 v[12:15], v[224:227], v[204:207], v[12:15]
	v_mfma_f32_16x16x32_bf16 v[8:11], v[228:231], v[204:207], v[8:11]
	v_mfma_f32_16x16x32_bf16 v[4:7], v[232:235], v[204:207], v[4:7]
	v_mfma_f32_16x16x32_bf16 v[0:3], v[236:239], v[204:207], v[0:3]
	s_nop 7
	s_nop 3
	s_branch .LBB0_1093

.LBB0_1136:
	v_add_u32_e32 v172, v153, v170
	v_add_u32_e32 v173, v153, v171
	v_add_u32_e32 v174, v169, v170
	v_add_u32_e32 v175, v169, v171
	s_mov_b64 s[100:101], 0x80
	v_lshl_add_u64 v[240:241], v[128:129], 0, s[100:101]
	s_mov_b64 s[100:101], 0x20080
	v_lshl_add_u64 v[242:243], v[128:129], 0, s[100:101]
	s_mov_b64 s[100:101], 0x40080
	v_lshl_add_u64 v[244:245], v[128:129], 0, s[100:101]
	s_mov_b64 s[100:101], 0x60080
	v_lshl_add_u64 v[246:247], v[128:129], 0, s[100:101]
	s_mov_b64 s[100:101], 0x80
	v_lshl_add_u64 v[138:139], v[130:131], 0, s[100:101]
	s_mov_b64 s[100:101], 0x20080
	v_lshl_add_u64 v[140:141], v[130:131], 0, s[100:101]
	s_mov_b64 s[100:101], 0x40080
	v_lshl_add_u64 v[250:251], v[130:131], 0, s[100:101]
	s_mov_b64 s[100:101], 0x60080
	v_lshl_add_u64 v[252:253], v[130:131], 0, s[100:101]
	v_readfirstlane_b32 s100, v144
	v_readfirstlane_b32 s101, v145
	s_nop 3
	ds_read_b128 v[176:179], v172 offset:0
	ds_read_b128 v[180:183], v172 offset:2048
	ds_read_b128 v[184:187], v172 offset:4096
	ds_read_b128 v[188:191], v172 offset:6144
	ds_read_b128 v[208:211], v174 offset:0
	ds_read_b128 v[212:215], v174 offset:2048
	ds_read_b128 v[216:219], v174 offset:4096
	ds_read_b128 v[220:223], v174 offset:6144
	s_add_u32 m0, s100, 0x8000
	s_nop 0
	global_load_lds_dwordx4 v[240:241], off
	v_lshl_add_u64 v[240:241], v[240:241], 0, s[34:35]
	s_add_u32 m0, s100, 0xa000
	s_nop 0
	global_load_lds_dwordx4 v[242:243], off
	v_lshl_add_u64 v[242:243], v[242:243], 0, s[34:35]
	s_add_u32 m0, s100, 0xc000
	s_nop 0
	global_load_lds_dwordx4 v[244:245], off
	v_lshl_add_u64 v[244:245], v[244:245], 0, s[34:35]
	s_add_u32 m0, s100, 0xe000
	s_nop 0
	global_load_lds_dwordx4 v[246:247], off
	v_lshl_add_u64 v[246:247], v[246:247], 0, s[34:35]
	s_waitcnt lgkmcnt(0)
	v_mfma_f32_16x16x32_bf16 v[124:127], v[208:211], v[176:179], v[124:127]
	ds_read_b128 v[224:227], v174 offset:8192
	v_mfma_f32_16x16x32_bf16 v[120:123], v[212:215], v[176:179], v[120:123]
	ds_read_b128 v[228:231], v174 offset:10240
	v_mfma_f32_16x16x32_bf16 v[116:119], v[216:219], v[176:179], v[116:119]
	ds_read_b128 v[232:235], v174 offset:12288
	v_mfma_f32_16x16x32_bf16 v[112:115], v[220:223], v[176:179], v[112:115]
	ds_read_b128 v[236:239], v174 offset:14336
	v_mfma_f32_16x16x32_bf16 v[92:95], v[208:211], v[180:183], v[92:95]
	s_add_u32 m0, s101, 0x8000
	v_mfma_f32_16x16x32_bf16 v[88:91], v[212:215], v[180:183], v[88:91]
	global_load_lds_dwordx4 v[138:139], off
	v_lshl_add_u64 v[138:139], v[138:139], 0, s[34:35]
	v_mfma_f32_16x16x32_bf16 v[84:87], v[216:219], v[180:183], v[84:87]
	s_add_u32 m0, s101, 0xa000
	v_mfma_f32_16x16x32_bf16 v[80:83], v[220:223], v[180:183], v[80:83]
	global_load_lds_dwordx4 v[140:141], off
	v_lshl_add_u64 v[140:141], v[140:141], 0, s[34:35]
	v_mfma_f32_16x16x32_bf16 v[60:63], v[208:211], v[184:187], v[60:63]
	s_add_u32 m0, s101, 0xc000
	v_mfma_f32_16x16x32_bf16 v[56:59], v[212:215], v[184:187], v[56:59]
	global_load_lds_dwordx4 v[250:251], off
	v_lshl_add_u64 v[250:251], v[250:251], 0, s[34:35]
	v_mfma_f32_16x16x32_bf16 v[52:55], v[216:219], v[184:187], v[52:55]
	s_add_u32 m0, s101, 0xe000
	v_mfma_f32_16x16x32_bf16 v[48:51], v[220:223], v[184:187], v[48:51]
	global_load_lds_dwordx4 v[252:253], off
	v_lshl_add_u64 v[252:253], v[252:253], 0, s[34:35]
	v_mfma_f32_16x16x32_bf16 v[28:31], v[208:211], v[188:191], v[28:31]
	v_mfma_f32_16x16x32_bf16 v[24:27], v[212:215], v[188:191], v[24:27]
	v_mfma_f32_16x16x32_bf16 v[20:23], v[216:219], v[188:191], v[20:23]
	v_mfma_f32_16x16x32_bf16 v[16:19], v[220:223], v[188:191], v[16:19]
	s_waitcnt lgkmcnt(0)
	v_mfma_f32_16x16x32_bf16 v[108:111], v[224:227], v[176:179], v[108:111]
	ds_read_b128 v[192:195], v173 offset:0
	v_mfma_f32_16x16x32_bf16 v[104:107], v[228:231], v[176:179], v[104:107]
	ds_read_b128 v[196:199], v173 offset:2048
	v_mfma_f32_16x16x32_bf16 v[100:103], v[232:235], v[176:179], v[100:103]
	ds_read_b128 v[200:203], v173 offset:4096
	v_mfma_f32_16x16x32_bf16 v[96:99], v[236:239], v[176:179], v[96:99]
	ds_read_b128 v[204:207], v173 offset:6144
	v_mfma_f32_16x16x32_bf16 v[76:79], v[224:227], v[180:183], v[76:79]
	ds_read_b128 v[208:211], v175 offset:0
	v_mfma_f32_16x16x32_bf16 v[72:75], v[228:231], v[180:183], v[72:75]
	ds_read_b128 v[212:215], v175 offset:2048
	v_mfma_f32_16x16x32_bf16 v[68:71], v[232:235], v[180:183], v[68:71]
	ds_read_b128 v[216:219], v175 offset:4096
	v_mfma_f32_16x16x32_bf16 v[64:67], v[236:239], v[180:183], v[64:67]
	ds_read_b128 v[220:223], v175 offset:6144
	v_mfma_f32_16x16x32_bf16 v[44:47], v[224:227], v[184:187], v[44:47]
	v_mfma_f32_16x16x32_bf16 v[40:43], v[228:231], v[184:187], v[40:43]
	v_mfma_f32_16x16x32_bf16 v[36:39], v[232:235], v[184:187], v[36:39]
	v_mfma_f32_16x16x32_bf16 v[32:35], v[236:239], v[184:187], v[32:35]
	v_mfma_f32_16x16x32_bf16 v[12:15], v[224:227], v[188:191], v[12:15]
	v_mfma_f32_16x16x32_bf16 v[8:11], v[228:231], v[188:191], v[8:11]
	v_mfma_f32_16x16x32_bf16 v[4:7], v[232:235], v[188:191], v[4:7]
	v_mfma_f32_16x16x32_bf16 v[0:3], v[236:239], v[188:191], v[0:3]
	s_waitcnt lgkmcnt(0)
	v_mfma_f32_16x16x32_bf16 v[124:127], v[208:211], v[192:195], v[124:127]
	ds_read_b128 v[224:227], v175 offset:8192
	v_mfma_f32_16x16x32_bf16 v[120:123], v[212:215], v[192:195], v[120:123]
	ds_read_b128 v[228:231], v175 offset:10240
	v_mfma_f32_16x16x32_bf16 v[116:119], v[216:219], v[192:195], v[116:119]
	ds_read_b128 v[232:235], v175 offset:12288
	v_mfma_f32_16x16x32_bf16 v[112:115], v[220:223], v[192:195], v[112:115]
	ds_read_b128 v[236:239], v175 offset:14336
	v_mfma_f32_16x16x32_bf16 v[92:95], v[208:211], v[196:199], v[92:95]
	v_mfma_f32_16x16x32_bf16 v[88:91], v[212:215], v[196:199], v[88:91]
	v_mfma_f32_16x16x32_bf16 v[84:87], v[216:219], v[196:199], v[84:87]
	v_mfma_f32_16x16x32_bf16 v[80:83], v[220:223], v[196:199], v[80:83]
	v_mfma_f32_16x16x32_bf16 v[60:63], v[208:211], v[200:203], v[60:63]
	v_mfma_f32_16x16x32_bf16 v[56:59], v[212:215], v[200:203], v[56:59]
	v_mfma_f32_16x16x32_bf16 v[52:55], v[216:219], v[200:203], v[52:55]
	v_mfma_f32_16x16x32_bf16 v[48:51], v[220:223], v[200:203], v[48:51]
	v_mfma_f32_16x16x32_bf16 v[28:31], v[208:211], v[204:207], v[28:31]
	v_mfma_f32_16x16x32_bf16 v[24:27], v[212:215], v[204:207], v[24:27]
	v_mfma_f32_16x16x32_bf16 v[20:23], v[216:219], v[204:207], v[20:23]
	v_mfma_f32_16x16x32_bf16 v[16:19], v[220:223], v[204:207], v[16:19]
	s_waitcnt lgkmcnt(0)
	s_waitcnt vmcnt(0)
	s_barrier
	s_mov_b32 s44, 7
.Lgemm_p9_loop:
	v_mfma_f32_16x16x32_bf16 v[108:111], v[224:227], v[192:195], v[108:111]
	ds_read_b128 v[176:179], v172 offset:32768
	v_mfma_f32_16x16x32_bf16 v[104:107], v[228:231], v[192:195], v[104:107]
	ds_read_b128 v[180:183], v172 offset:34816
	v_mfma_f32_16x16x32_bf16 v[100:103], v[232:235], v[192:195], v[100:103]
	ds_read_b128 v[184:187], v172 offset:36864
	v_mfma_f32_16x16x32_bf16 v[96:99], v[236:239], v[192:195], v[96:99]
	ds_read_b128 v[188:191], v172 offset:38912
	v_mfma_f32_16x16x32_bf16 v[76:79], v[224:227], v[196:199], v[76:79]
	ds_read_b128 v[208:211], v174 offset:32768
	v_mfma_f32_16x16x32_bf16 v[72:75], v[228:231], v[196:199], v[72:75]
	ds_read_b128 v[212:215], v174 offset:34816
	v_mfma_f32_16x16x32_bf16 v[68:71], v[232:235], v[196:199], v[68:71]
	ds_read_b128 v[216:219], v174 offset:36864
	v_mfma_f32_16x16x32_bf16 v[64:67], v[236:239], v[196:199], v[64:67]
	ds_read_b128 v[220:223], v174 offset:38912
	v_mfma_f32_16x16x32_bf16 v[44:47], v[224:227], v[200:203], v[44:47]
	s_mov_b32 m0, s100
	v_mfma_f32_16x16x32_bf16 v[40:43], v[228:231], v[200:203], v[40:43]
	global_load_lds_dwordx4 v[240:241], off
	v_lshl_add_u64 v[240:241], v[240:241], 0, s[34:35]
	v_mfma_f32_16x16x32_bf16 v[36:39], v[232:235], v[200:203], v[36:39]
	s_add_u32 m0, s100, 0x2000
	v_mfma_f32_16x16x32_bf16 v[32:35], v[236:239], v[200:203], v[32:35]
	global_load_lds_dwordx4 v[242:243], off
	v_lshl_add_u64 v[242:243], v[242:243], 0, s[34:35]
	v_mfma_f32_16x16x32_bf16 v[12:15], v[224:227], v[204:207], v[12:15]
	s_add_u32 m0, s100, 0x4000
	v_mfma_f32_16x16x32_bf16 v[8:11], v[228:231], v[204:207], v[8:11]
	global_load_lds_dwordx4 v[244:245], off
	v_lshl_add_u64 v[244:245], v[244:245], 0, s[34:35]
	v_mfma_f32_16x16x32_bf16 v[4:7], v[232:235], v[204:207], v[4:7]
	s_add_u32 m0, s100, 0x6000
	v_mfma_f32_16x16x32_bf16 v[0:3], v[236:239], v[204:207], v[0:3]
	global_load_lds_dwordx4 v[246:247], off
	v_lshl_add_u64 v[246:247], v[246:247], 0, s[34:35]
	s_waitcnt lgkmcnt(0)
	v_mfma_f32_16x16x32_bf16 v[124:127], v[208:211], v[176:179], v[124:127]
	ds_read_b128 v[224:227], v174 offset:40960
	v_mfma_f32_16x16x32_bf16 v[120:123], v[212:215], v[176:179], v[120:123]
	ds_read_b128 v[228:231], v174 offset:43008
	v_mfma_f32_16x16x32_bf16 v[116:119], v[216:219], v[176:179], v[116:119]
	ds_read_b128 v[232:235], v174 offset:45056
	v_mfma_f32_16x16x32_bf16 v[112:115], v[220:223], v[176:179], v[112:115]
	ds_read_b128 v[236:239], v174 offset:47104
	v_mfma_f32_16x16x32_bf16 v[92:95], v[208:211], v[180:183], v[92:95]
	s_mov_b32 m0, s101
	v_mfma_f32_16x16x32_bf16 v[88:91], v[212:215], v[180:183], v[88:91]
	global_load_lds_dwordx4 v[138:139], off
	v_lshl_add_u64 v[138:139], v[138:139], 0, s[34:35]
	v_mfma_f32_16x16x32_bf16 v[84:87], v[216:219], v[180:183], v[84:87]
	s_add_u32 m0, s101, 0x2000
	v_mfma_f32_16x16x32_bf16 v[80:83], v[220:223], v[180:183], v[80:83]
	global_load_lds_dwordx4 v[140:141], off
	v_lshl_add_u64 v[140:141], v[140:141], 0, s[34:35]
	v_mfma_f32_16x16x32_bf16 v[60:63], v[208:211], v[184:187], v[60:63]
	s_add_u32 m0, s101, 0x4000
	v_mfma_f32_16x16x32_bf16 v[56:59], v[212:215], v[184:187], v[56:59]
	global_load_lds_dwordx4 v[250:251], off
	v_lshl_add_u64 v[250:251], v[250:251], 0, s[34:35]
	v_mfma_f32_16x16x32_bf16 v[52:55], v[216:219], v[184:187], v[52:55]
	s_add_u32 m0, s101, 0x6000
	v_mfma_f32_16x16x32_bf16 v[48:51], v[220:223], v[184:187], v[48:51]
	global_load_lds_dwordx4 v[252:253], off
	v_lshl_add_u64 v[252:253], v[252:253], 0, s[34:35]
	v_mfma_f32_16x16x32_bf16 v[28:31], v[208:211], v[188:191], v[28:31]
	v_mfma_f32_16x16x32_bf16 v[24:27], v[212:215], v[188:191], v[24:27]
	v_mfma_f32_16x16x32_bf16 v[20:23], v[216:219], v[188:191], v[20:23]
	v_mfma_f32_16x16x32_bf16 v[16:19], v[220:223], v[188:191], v[16:19]
	s_waitcnt lgkmcnt(0)
	v_mfma_f32_16x16x32_bf16 v[108:111], v[224:227], v[176:179], v[108:111]
	ds_read_b128 v[192:195], v173 offset:32768
	v_mfma_f32_16x16x32_bf16 v[104:107], v[228:231], v[176:179], v[104:107]
	ds_read_b128 v[196:199], v173 offset:34816
	v_mfma_f32_16x16x32_bf16 v[100:103], v[232:235], v[176:179], v[100:103]
	ds_read_b128 v[200:203], v173 offset:36864
	v_mfma_f32_16x16x32_bf16 v[96:99], v[236:239], v[176:179], v[96:99]
	ds_read_b128 v[204:207], v173 offset:38912
	v_mfma_f32_16x16x32_bf16 v[76:79], v[224:227], v[180:183], v[76:79]
	ds_read_b128 v[208:211], v175 offset:32768
	v_mfma_f32_16x16x32_bf16 v[72:75], v[228:231], v[180:183], v[72:75]
	ds_read_b128 v[212:215], v175 offset:34816
	v_mfma_f32_16x16x32_bf16 v[68:71], v[232:235], v[180:183], v[68:71]
	ds_read_b128 v[216:219], v175 offset:36864
	v_mfma_f32_16x16x32_bf16 v[64:67], v[236:239], v[180:183], v[64:67]
	ds_read_b128 v[220:223], v175 offset:38912
	v_mfma_f32_16x16x32_bf16 v[44:47], v[224:227], v[184:187], v[44:47]
	v_mfma_f32_16x16x32_bf16 v[40:43], v[228:231], v[184:187], v[40:43]
	v_mfma_f32_16x16x32_bf16 v[36:39], v[232:235], v[184:187], v[36:39]
	v_mfma_f32_16x16x32_bf16 v[32:35], v[236:239], v[184:187], v[32:35]
	v_mfma_f32_16x16x32_bf16 v[12:15], v[224:227], v[188:191], v[12:15]
	v_mfma_f32_16x16x32_bf16 v[8:11], v[228:231], v[188:191], v[8:11]
	v_mfma_f32_16x16x32_bf16 v[4:7], v[232:235], v[188:191], v[4:7]
	v_mfma_f32_16x16x32_bf16 v[0:3], v[236:239], v[188:191], v[0:3]
	s_waitcnt lgkmcnt(0)
	v_mfma_f32_16x16x32_bf16 v[124:127], v[208:211], v[192:195], v[124:127]
	ds_read_b128 v[224:227], v175 offset:40960
	v_mfma_f32_16x16x32_bf16 v[120:123], v[212:215], v[192:195], v[120:123]
	ds_read_b128 v[228:231], v175 offset:43008
	v_mfma_f32_16x16x32_bf16 v[116:119], v[216:219], v[192:195], v[116:119]
	ds_read_b128 v[232:235], v175 offset:45056
	v_mfma_f32_16x16x32_bf16 v[112:115], v[220:223], v[192:195], v[112:115]
	ds_read_b128 v[236:239], v175 offset:47104
	v_mfma_f32_16x16x32_bf16 v[92:95], v[208:211], v[196:199], v[92:95]
	v_mfma_f32_16x16x32_bf16 v[88:91], v[212:215], v[196:199], v[88:91]
	v_mfma_f32_16x16x32_bf16 v[84:87], v[216:219], v[196:199], v[84:87]
	v_mfma_f32_16x16x32_bf16 v[80:83], v[220:223], v[196:199], v[80:83]
	v_mfma_f32_16x16x32_bf16 v[60:63], v[208:211], v[200:203], v[60:63]
	v_mfma_f32_16x16x32_bf16 v[56:59], v[212:215], v[200:203], v[56:59]
	v_mfma_f32_16x16x32_bf16 v[52:55], v[216:219], v[200:203], v[52:55]
	v_mfma_f32_16x16x32_bf16 v[48:51], v[220:223], v[200:203], v[48:51]
	v_mfma_f32_16x16x32_bf16 v[28:31], v[208:211], v[204:207], v[28:31]
	v_mfma_f32_16x16x32_bf16 v[24:27], v[212:215], v[204:207], v[24:27]
	v_mfma_f32_16x16x32_bf16 v[20:23], v[216:219], v[204:207], v[20:23]
	v_mfma_f32_16x16x32_bf16 v[16:19], v[220:223], v[204:207], v[16:19]
	s_waitcnt lgkmcnt(0)
	s_waitcnt vmcnt(0)
	s_barrier
	v_mfma_f32_16x16x32_bf16 v[108:111], v[224:227], v[192:195], v[108:111]
	ds_read_b128 v[176:179], v172 offset:0
	v_mfma_f32_16x16x32_bf16 v[104:107], v[228:231], v[192:195], v[104:107]
	ds_read_b128 v[180:183], v172 offset:2048
	v_mfma_f32_16x16x32_bf16 v[100:103], v[232:235], v[192:195], v[100:103]
	ds_read_b128 v[184:187], v172 offset:4096
	v_mfma_f32_16x16x32_bf16 v[96:99], v[236:239], v[192:195], v[96:99]
	ds_read_b128 v[188:191], v172 offset:6144
	v_mfma_f32_16x16x32_bf16 v[76:79], v[224:227], v[196:199], v[76:79]
	ds_read_b128 v[208:211], v174 offset:0
	v_mfma_f32_16x16x32_bf16 v[72:75], v[228:231], v[196:199], v[72:75]
	ds_read_b128 v[212:215], v174 offset:2048
	v_mfma_f32_16x16x32_bf16 v[68:71], v[232:235], v[196:199], v[68:71]
	ds_read_b128 v[216:219], v174 offset:4096
	v_mfma_f32_16x16x32_bf16 v[64:67], v[236:239], v[196:199], v[64:67]
	ds_read_b128 v[220:223], v174 offset:6144
	v_mfma_f32_16x16x32_bf16 v[44:47], v[224:227], v[200:203], v[44:47]
	s_add_u32 m0, s100, 0x8000
	v_mfma_f32_16x16x32_bf16 v[40:43], v[228:231], v[200:203], v[40:43]
	global_load_lds_dwordx4 v[240:241], off
	v_lshl_add_u64 v[240:241], v[240:241], 0, s[34:35]
	v_mfma_f32_16x16x32_bf16 v[36:39], v[232:235], v[200:203], v[36:39]
	s_add_u32 m0, s100, 0xa000
	v_mfma_f32_16x16x32_bf16 v[32:35], v[236:239], v[200:203], v[32:35]
	global_load_lds_dwordx4 v[242:243], off
	v_lshl_add_u64 v[242:243], v[242:243], 0, s[34:35]
	v_mfma_f32_16x16x32_bf16 v[12:15], v[224:227], v[204:207], v[12:15]
	s_add_u32 m0, s100, 0xc000
	v_mfma_f32_16x16x32_bf16 v[8:11], v[228:231], v[204:207], v[8:11]
	global_load_lds_dwordx4 v[244:245], off
	v_lshl_add_u64 v[244:245], v[244:245], 0, s[34:35]
	v_mfma_f32_16x16x32_bf16 v[4:7], v[232:235], v[204:207], v[4:7]
	s_add_u32 m0, s100, 0xe000
	v_mfma_f32_16x16x32_bf16 v[0:3], v[236:239], v[204:207], v[0:3]
	global_load_lds_dwordx4 v[246:247], off
	v_lshl_add_u64 v[246:247], v[246:247], 0, s[34:35]
	s_waitcnt lgkmcnt(0)
	v_mfma_f32_16x16x32_bf16 v[124:127], v[208:211], v[176:179], v[124:127]
	ds_read_b128 v[224:227], v174 offset:8192
	v_mfma_f32_16x16x32_bf16 v[120:123], v[212:215], v[176:179], v[120:123]
	ds_read_b128 v[228:231], v174 offset:10240
	v_mfma_f32_16x16x32_bf16 v[116:119], v[216:219], v[176:179], v[116:119]
	ds_read_b128 v[232:235], v174 offset:12288
	v_mfma_f32_16x16x32_bf16 v[112:115], v[220:223], v[176:179], v[112:115]
	ds_read_b128 v[236:239], v174 offset:14336
	v_mfma_f32_16x16x32_bf16 v[92:95], v[208:211], v[180:183], v[92:95]
	s_add_u32 m0, s101, 0x8000
	v_mfma_f32_16x16x32_bf16 v[88:91], v[212:215], v[180:183], v[88:91]
	global_load_lds_dwordx4 v[138:139], off
	v_lshl_add_u64 v[138:139], v[138:139], 0, s[34:35]
	v_mfma_f32_16x16x32_bf16 v[84:87], v[216:219], v[180:183], v[84:87]
	s_add_u32 m0, s101, 0xa000
	v_mfma_f32_16x16x32_bf16 v[80:83], v[220:223], v[180:183], v[80:83]
	global_load_lds_dwordx4 v[140:141], off
	v_lshl_add_u64 v[140:141], v[140:141], 0, s[34:35]
	v_mfma_f32_16x16x32_bf16 v[60:63], v[208:211], v[184:187], v[60:63]
	s_add_u32 m0, s101, 0xc000
	v_mfma_f32_16x16x32_bf16 v[56:59], v[212:215], v[184:187], v[56:59]
	global_load_lds_dwordx4 v[250:251], off
	v_lshl_add_u64 v[250:251], v[250:251], 0, s[34:35]
	v_mfma_f32_16x16x32_bf16 v[52:55], v[216:219], v[184:187], v[52:55]
	s_add_u32 m0, s101, 0xe000
	v_mfma_f32_16x16x32_bf16 v[48:51], v[220:223], v[184:187], v[48:51]
	global_load_lds_dwordx4 v[252:253], off
	v_lshl_add_u64 v[252:253], v[252:253], 0, s[34:35]
	v_mfma_f32_16x16x32_bf16 v[28:31], v[208:211], v[188:191], v[28:31]
	v_mfma_f32_16x16x32_bf16 v[24:27], v[212:215], v[188:191], v[24:27]
	v_mfma_f32_16x16x32_bf16 v[20:23], v[216:219], v[188:191], v[20:23]
	v_mfma_f32_16x16x32_bf16 v[16:19], v[220:223], v[188:191], v[16:19]
	s_waitcnt lgkmcnt(0)
	v_mfma_f32_16x16x32_bf16 v[108:111], v[224:227], v[176:179], v[108:111]
	ds_read_b128 v[192:195], v173 offset:0
	v_mfma_f32_16x16x32_bf16 v[104:107], v[228:231], v[176:179], v[104:107]
	ds_read_b128 v[196:199], v173 offset:2048
	v_mfma_f32_16x16x32_bf16 v[100:103], v[232:235], v[176:179], v[100:103]
	ds_read_b128 v[200:203], v173 offset:4096
	v_mfma_f32_16x16x32_bf16 v[96:99], v[236:239], v[176:179], v[96:99]
	ds_read_b128 v[204:207], v173 offset:6144
	v_mfma_f32_16x16x32_bf16 v[76:79], v[224:227], v[180:183], v[76:79]
	ds_read_b128 v[208:211], v175 offset:0
	v_mfma_f32_16x16x32_bf16 v[72:75], v[228:231], v[180:183], v[72:75]
	ds_read_b128 v[212:215], v175 offset:2048
	v_mfma_f32_16x16x32_bf16 v[68:71], v[232:235], v[180:183], v[68:71]
	ds_read_b128 v[216:219], v175 offset:4096
	v_mfma_f32_16x16x32_bf16 v[64:67], v[236:239], v[180:183], v[64:67]
	ds_read_b128 v[220:223], v175 offset:6144
	v_mfma_f32_16x16x32_bf16 v[44:47], v[224:227], v[184:187], v[44:47]
	v_mfma_f32_16x16x32_bf16 v[40:43], v[228:231], v[184:187], v[40:43]
	v_mfma_f32_16x16x32_bf16 v[36:39], v[232:235], v[184:187], v[36:39]
	v_mfma_f32_16x16x32_bf16 v[32:35], v[236:239], v[184:187], v[32:35]
	v_mfma_f32_16x16x32_bf16 v[12:15], v[224:227], v[188:191], v[12:15]
	v_mfma_f32_16x16x32_bf16 v[8:11], v[228:231], v[188:191], v[8:11]
	v_mfma_f32_16x16x32_bf16 v[4:7], v[232:235], v[188:191], v[4:7]
	v_mfma_f32_16x16x32_bf16 v[0:3], v[236:239], v[188:191], v[0:3]
	s_waitcnt lgkmcnt(0)
	v_mfma_f32_16x16x32_bf16 v[124:127], v[208:211], v[192:195], v[124:127]
	ds_read_b128 v[224:227], v175 offset:8192
	v_mfma_f32_16x16x32_bf16 v[120:123], v[212:215], v[192:195], v[120:123]
	ds_read_b128 v[228:231], v175 offset:10240
	v_mfma_f32_16x16x32_bf16 v[116:119], v[216:219], v[192:195], v[116:119]
	ds_read_b128 v[232:235], v175 offset:12288
	v_mfma_f32_16x16x32_bf16 v[112:115], v[220:223], v[192:195], v[112:115]
	ds_read_b128 v[236:239], v175 offset:14336
	v_mfma_f32_16x16x32_bf16 v[92:95], v[208:211], v[196:199], v[92:95]
	v_mfma_f32_16x16x32_bf16 v[88:91], v[212:215], v[196:199], v[88:91]
	v_mfma_f32_16x16x32_bf16 v[84:87], v[216:219], v[196:199], v[84:87]
	v_mfma_f32_16x16x32_bf16 v[80:83], v[220:223], v[196:199], v[80:83]
	v_mfma_f32_16x16x32_bf16 v[60:63], v[208:211], v[200:203], v[60:63]
	v_mfma_f32_16x16x32_bf16 v[56:59], v[212:215], v[200:203], v[56:59]
	v_mfma_f32_16x16x32_bf16 v[52:55], v[216:219], v[200:203], v[52:55]
	v_mfma_f32_16x16x32_bf16 v[48:51], v[220:223], v[200:203], v[48:51]
	v_mfma_f32_16x16x32_bf16 v[28:31], v[208:211], v[204:207], v[28:31]
	v_mfma_f32_16x16x32_bf16 v[24:27], v[212:215], v[204:207], v[24:27]
	v_mfma_f32_16x16x32_bf16 v[20:23], v[216:219], v[204:207], v[20:23]
	v_mfma_f32_16x16x32_bf16 v[16:19], v[220:223], v[204:207], v[16:19]
	s_waitcnt lgkmcnt(0)
	s_waitcnt vmcnt(0)
	s_barrier
	s_add_i32 s44, s44, -1
	s_cmp_lg_u32 s44, 0
	s_cbranch_scc1 .Lgemm_p9_loop
	v_mfma_f32_16x16x32_bf16 v[108:111], v[224:227], v[192:195], v[108:111]
	ds_read_b128 v[176:179], v172 offset:32768
	v_mfma_f32_16x16x32_bf16 v[104:107], v[228:231], v[192:195], v[104:107]
	ds_read_b128 v[180:183], v172 offset:34816
	v_mfma_f32_16x16x32_bf16 v[100:103], v[232:235], v[192:195], v[100:103]
	ds_read_b128 v[184:187], v172 offset:36864
	v_mfma_f32_16x16x32_bf16 v[96:99], v[236:239], v[192:195], v[96:99]
	ds_read_b128 v[188:191], v172 offset:38912
	v_mfma_f32_16x16x32_bf16 v[76:79], v[224:227], v[196:199], v[76:79]
	ds_read_b128 v[208:211], v174 offset:32768
	v_mfma_f32_16x16x32_bf16 v[72:75], v[228:231], v[196:199], v[72:75]
	ds_read_b128 v[212:215], v174 offset:34816
	v_mfma_f32_16x16x32_bf16 v[68:71], v[232:235], v[196:199], v[68:71]
	ds_read_b128 v[216:219], v174 offset:36864
	v_mfma_f32_16x16x32_bf16 v[64:67], v[236:239], v[196:199], v[64:67]
	ds_read_b128 v[220:223], v174 offset:38912
	v_mfma_f32_16x16x32_bf16 v[44:47], v[224:227], v[200:203], v[44:47]
	v_mfma_f32_16x16x32_bf16 v[40:43], v[228:231], v[200:203], v[40:43]
	v_mfma_f32_16x16x32_bf16 v[36:39], v[232:235], v[200:203], v[36:39]
	v_mfma_f32_16x16x32_bf16 v[32:35], v[236:239], v[200:203], v[32:35]
	v_mfma_f32_16x16x32_bf16 v[12:15], v[224:227], v[204:207], v[12:15]
	v_mfma_f32_16x16x32_bf16 v[8:11], v[228:231], v[204:207], v[8:11]
	v_mfma_f32_16x16x32_bf16 v[4:7], v[232:235], v[204:207], v[4:7]
	v_mfma_f32_16x16x32_bf16 v[0:3], v[236:239], v[204:207], v[0:3]
	s_waitcnt lgkmcnt(0)
	v_mfma_f32_16x16x32_bf16 v[124:127], v[208:211], v[176:179], v[124:127]
	ds_read_b128 v[224:227], v174 offset:40960
	v_mfma_f32_16x16x32_bf16 v[120:123], v[212:215], v[176:179], v[120:123]
	ds_read_b128 v[228:231], v174 offset:43008
	v_mfma_f32_16x16x32_bf16 v[116:119], v[216:219], v[176:179], v[116:119]
	ds_read_b128 v[232:235], v174 offset:45056
	v_mfma_f32_16x16x32_bf16 v[112:115], v[220:223], v[176:179], v[112:115]
	ds_read_b128 v[236:239], v174 offset:47104
	v_mfma_f32_16x16x32_bf16 v[92:95], v[208:211], v[180:183], v[92:95]
	v_mfma_f32_16x16x32_bf16 v[88:91], v[212:215], v[180:183], v[88:91]
	v_mfma_f32_16x16x32_bf16 v[84:87], v[216:219], v[180:183], v[84:87]
	v_mfma_f32_16x16x32_bf16 v[80:83], v[220:223], v[180:183], v[80:83]
	v_mfma_f32_16x16x32_bf16 v[60:63], v[208:211], v[184:187], v[60:63]
	v_mfma_f32_16x16x32_bf16 v[56:59], v[212:215], v[184:187], v[56:59]
	v_mfma_f32_16x16x32_bf16 v[52:55], v[216:219], v[184:187], v[52:55]
	v_mfma_f32_16x16x32_bf16 v[48:51], v[220:223], v[184:187], v[48:51]
	v_mfma_f32_16x16x32_bf16 v[28:31], v[208:211], v[188:191], v[28:31]
	v_mfma_f32_16x16x32_bf16 v[24:27], v[212:215], v[188:191], v[24:27]
	v_mfma_f32_16x16x32_bf16 v[20:23], v[216:219], v[188:191], v[20:23]
	v_mfma_f32_16x16x32_bf16 v[16:19], v[220:223], v[188:191], v[16:19]
	s_waitcnt lgkmcnt(0)
	v_mfma_f32_16x16x32_bf16 v[108:111], v[224:227], v[176:179], v[108:111]
	ds_read_b128 v[192:195], v173 offset:32768
	v_mfma_f32_16x16x32_bf16 v[104:107], v[228:231], v[176:179], v[104:107]
	ds_read_b128 v[196:199], v173 offset:34816
	v_mfma_f32_16x16x32_bf16 v[100:103], v[232:235], v[176:179], v[100:103]
	ds_read_b128 v[200:203], v173 offset:36864
	v_mfma_f32_16x16x32_bf16 v[96:99], v[236:239], v[176:179], v[96:99]
	ds_read_b128 v[204:207], v173 offset:38912
	v_mfma_f32_16x16x32_bf16 v[76:79], v[224:227], v[180:183], v[76:79]
	ds_read_b128 v[208:211], v175 offset:32768
	v_mfma_f32_16x16x32_bf16 v[72:75], v[228:231], v[180:183], v[72:75]
	ds_read_b128 v[212:215], v175 offset:34816
	v_mfma_f32_16x16x32_bf16 v[68:71], v[232:235], v[180:183], v[68:71]
	ds_read_b128 v[216:219], v175 offset:36864
	v_mfma_f32_16x16x32_bf16 v[64:67], v[236:239], v[180:183], v[64:67]
	ds_read_b128 v[220:223], v175 offset:38912
	v_mfma_f32_16x16x32_bf16 v[44:47], v[224:227], v[184:187], v[44:47]
	v_mfma_f32_16x16x32_bf16 v[40:43], v[228:231], v[184:187], v[40:43]
	v_mfma_f32_16x16x32_bf16 v[36:39], v[232:235], v[184:187], v[36:39]
	v_mfma_f32_16x16x32_bf16 v[32:35], v[236:239], v[184:187], v[32:35]
	v_mfma_f32_16x16x32_bf16 v[12:15], v[224:227], v[188:191], v[12:15]
	v_mfma_f32_16x16x32_bf16 v[8:11], v[228:231], v[188:191], v[8:11]
	v_mfma_f32_16x16x32_bf16 v[4:7], v[232:235], v[188:191], v[4:7]
	v_mfma_f32_16x16x32_bf16 v[0:3], v[236:239], v[188:191], v[0:3]
	s_waitcnt lgkmcnt(0)
	v_mfma_f32_16x16x32_bf16 v[124:127], v[208:211], v[192:195], v[124:127]
	ds_read_b128 v[224:227], v175 offset:40960
	v_mfma_f32_16x16x32_bf16 v[120:123], v[212:215], v[192:195], v[120:123]
	ds_read_b128 v[228:231], v175 offset:43008
	v_mfma_f32_16x16x32_bf16 v[116:119], v[216:219], v[192:195], v[116:119]
	ds_read_b128 v[232:235], v175 offset:45056
	v_mfma_f32_16x16x32_bf16 v[112:115], v[220:223], v[192:195], v[112:115]
	ds_read_b128 v[236:239], v175 offset:47104
	v_mfma_f32_16x16x32_bf16 v[92:95], v[208:211], v[196:199], v[92:95]
	v_mfma_f32_16x16x32_bf16 v[88:91], v[212:215], v[196:199], v[88:91]
	v_mfma_f32_16x16x32_bf16 v[84:87], v[216:219], v[196:199], v[84:87]
	v_mfma_f32_16x16x32_bf16 v[80:83], v[220:223], v[196:199], v[80:83]
	v_mfma_f32_16x16x32_bf16 v[60:63], v[208:211], v[200:203], v[60:63]
	v_mfma_f32_16x16x32_bf16 v[56:59], v[212:215], v[200:203], v[56:59]
	v_mfma_f32_16x16x32_bf16 v[52:55], v[216:219], v[200:203], v[52:55]
	v_mfma_f32_16x16x32_bf16 v[48:51], v[220:223], v[200:203], v[48:51]
	v_mfma_f32_16x16x32_bf16 v[28:31], v[208:211], v[204:207], v[28:31]
	v_mfma_f32_16x16x32_bf16 v[24:27], v[212:215], v[204:207], v[24:27]
	v_mfma_f32_16x16x32_bf16 v[20:23], v[216:219], v[204:207], v[20:23]
	v_mfma_f32_16x16x32_bf16 v[16:19], v[220:223], v[204:207], v[16:19]
	s_waitcnt lgkmcnt(0)
	v_mfma_f32_16x16x32_bf16 v[108:111], v[224:227], v[192:195], v[108:111]
	v_mfma_f32_16x16x32_bf16 v[104:107], v[228:231], v[192:195], v[104:107]
	v_mfma_f32_16x16x32_bf16 v[100:103], v[232:235], v[192:195], v[100:103]
	v_mfma_f32_16x16x32_bf16 v[96:99], v[236:239], v[192:195], v[96:99]
	v_mfma_f32_16x16x32_bf16 v[76:79], v[224:227], v[196:199], v[76:79]
	v_mfma_f32_16x16x32_bf16 v[72:75], v[228:231], v[196:199], v[72:75]
	v_mfma_f32_16x16x32_bf16 v[68:71], v[232:235], v[196:199], v[68:71]
	v_mfma_f32_16x16x32_bf16 v[64:67], v[236:239], v[196:199], v[64:67]
	v_mfma_f32_16x16x32_bf16 v[44:47], v[224:227], v[200:203], v[44:47]
	v_mfma_f32_16x16x32_bf16 v[40:43], v[228:231], v[200:203], v[40:43]
	v_mfma_f32_16x16x32_bf16 v[36:39], v[232:235], v[200:203], v[36:39]
	v_mfma_f32_16x16x32_bf16 v[32:35], v[236:239], v[200:203], v[32:35]
	v_mfma_f32_16x16x32_bf16 v[12:15], v[224:227], v[204:207], v[12:15]
	v_mfma_f32_16x16x32_bf16 v[8:11], v[228:231], v[204:207], v[8:11]
	v_mfma_f32_16x16x32_bf16 v[4:7], v[232:235], v[204:207], v[4:7]
	v_mfma_f32_16x16x32_bf16 v[0:3], v[236:239], v[204:207], v[0:3]
	s_nop 7
	s_nop 3
	s_branch .LBB0_1124
.LBB0_1138:
	s_waitcnt vmcnt(0) lgkmcnt(0)
	s_add_i32 s14, s14, s66
	s_barrier
	s_and_saveexec_b64 s[4:5], s[70:71]
	s_mov_b64 s[16:17], 0x10c0000
	s_mov_b64 s[18:19], 0x1fb00000
	s_cbranch_execz .LBB0_1144
	s_mov_b64 s[6:7], exec
	buffer_wbl2 sc1
	s_waitcnt vmcnt(0)
	s_waitcnt vmcnt(0)
	v_mbcnt_lo_u32_b32 v0, s6, 0
	v_mbcnt_hi_u32_b32 v0, s7, v0
	v_cmp_eq_u32_e32 vcc, 0, v0
	s_and_saveexec_b64 s[44:45], vcc
	s_cbranch_execz .LBB0_1141
	s_bcnt1_i32_b64 s6, s[6:7]
	v_mov_b32_e32 v0, s6
	v_readlane_b32 s6, v249, 3
	v_readlane_b32 s7, v249, 4
	s_nop 4
	global_atomic_add v135, v0, s[6:7]
